# v46 + f32->bf16 RNE bit trick (bfe/add3/lshr/and_or) replaced by v_cvt_pk_bf16_f32 at 196 pair sites (row phases, P0, P2) with store-data WAR pads + peeled first K-iteration per GEMM unit (no accumula
# speedup vs baseline: 1.0089x; 1.0085x over previous
.LBB0_30:
	s_cmpk_gt_u32 s61, 0x13ff
	s_cbranch_scc0 .LBB0_40
	s_mul_i32 s25, s22, 0x5d00000
	s_mul_hi_i32 s24, s22, 0x5d00000
	s_add_u32 s62, s14, s25
	s_addc_u32 s63, s15, s24
	s_cmpk_gt_u32 s61, 0x1bff
	s_mov_b64 s[24:25], -1
	s_cbranch_scc0 .LBB0_37
	s_lshl_b64 s[24:25], s[22:23], 26
	s_cmpk_gt_u32 s61, 0x3bff
	s_mov_b64 s[26:27], -1
	s_cbranch_scc0 .LBB0_34
	s_add_u32 s27, s6, s24
	s_addc_u32 s65, s7, s25
	s_add_i32 s26, s61, 0xc400
	s_and_b32 s66, s26, 0xffc0
	s_and_b32 s26, s31, 0x7e0
	s_lshl_b32 s64, s26, 2
	s_add_u32 s64, s27, s64
	v_or_b32_e32 v5, s66, v1
	s_addc_u32 s65, s65, 0
	v_lshl_add_u64 v[32:33], s[64:65], 0, v[2:3]
	v_lshlrev_b32_e32 v34, 13, v5
	v_mov_b32_e32 v35, v3
	v_lshl_add_u64 v[56:57], v[32:33], 0, v[34:35]
	v_add_co_u32_e32 v36, vcc, s35, v56
	s_nop 1
	v_addc_co_u32_e32 v37, vcc, 0, v57, vcc
	v_add_co_u32_e32 v40, vcc, s36, v56
	global_load_dwordx4 v[32:35], v[56:57], off
	s_nop 0
	global_load_dwordx4 v[36:39], v[36:37], off
	v_addc_co_u32_e32 v41, vcc, 0, v57, vcc
	v_add_co_u32_e32 v44, vcc, s37, v56
	s_nop 1
	v_addc_co_u32_e32 v45, vcc, 0, v57, vcc
	v_add_co_u32_e32 v48, vcc, s38, v56
	global_load_dwordx4 v[40:43], v[40:41], off
	s_nop 0
	global_load_dwordx4 v[44:47], v[44:45], off
	v_addc_co_u32_e32 v49, vcc, 0, v57, vcc
	v_add_co_u32_e32 v52, vcc, s39, v56
	s_nop 1
	v_addc_co_u32_e32 v53, vcc, 0, v57, vcc
	v_add_co_u32_e32 v58, vcc, s40, v56
	global_load_dwordx4 v[48:51], v[48:49], off
	s_nop 0
	global_load_dwordx4 v[52:55], v[52:53], off
	v_addc_co_u32_e32 v59, vcc, 0, v57, vcc
	v_add_co_u32_e32 v60, vcc, s41, v56
	s_nop 1
	v_addc_co_u32_e32 v61, vcc, 0, v57, vcc
	global_load_dwordx4 v[56:59], v[58:59], off
	s_nop 0
	global_load_dwordx4 v[60:63], v[60:61], off
	s_waitcnt vmcnt(7)
	ds_write2_b32 v10, v32, v33 offset1:1
	ds_write2_b32 v10, v34, v35 offset0:2 offset1:3
	s_waitcnt vmcnt(6)
	ds_write2_b32 v11, v36, v37 offset1:1
	ds_write2_b32 v12, v38, v39 offset1:1
	s_waitcnt vmcnt(5)
	ds_write2_b32 v13, v40, v41 offset1:1
	ds_write2_b32 v14, v42, v43 offset1:1
	s_waitcnt vmcnt(4)
	ds_write2_b32 v15, v44, v45 offset1:1
	ds_write2_b32 v16, v46, v47 offset1:1
	s_waitcnt vmcnt(3)
	ds_write2_b32 v17, v48, v49 offset1:1
	ds_write2_b32 v18, v50, v51 offset1:1
	s_waitcnt vmcnt(2)
	ds_write2_b32 v19, v52, v53 offset1:1
	ds_write2_b32 v20, v54, v55 offset1:1
	s_waitcnt vmcnt(1)
	ds_write2_b32 v21, v56, v57 offset1:1
	ds_write2_b32 v22, v58, v59 offset1:1
	s_waitcnt vmcnt(0)
	ds_write2_b32 v23, v60, v61 offset1:1
	ds_write2_b32 v24, v62, v63 offset1:1
	s_waitcnt lgkmcnt(0)
	ds_read2_b32 v[36:37], v9 offset1:8
	ds_read2_b32 v[40:41], v9 offset0:33 offset1:41
	s_lshl_b32 s27, s66, 1
	s_add_u32 s64, s62, s27
	ds_read2_b32 v[42:43], v9 offset0:66 offset1:74
	s_addc_u32 s65, s63, 0
	v_mov_b32_e32 v5, v3
	ds_read2_b32 v[44:45], v9 offset0:99 offset1:107
	v_lshl_add_u64 v[32:33], s[64:65], 0, v[4:5]
	s_waitcnt lgkmcnt(3)
	v_lshl_add_u64 v[38:39], v[32:33], 0, s[16:17]
	s_waitcnt lgkmcnt(2)
	ds_read2_b32 v[46:47], v9 offset0:132 offset1:140
	ds_read2_b32 v[48:49], v9 offset0:165 offset1:173
	v_cvt_pk_bf16_f32 v32, v36, v40
	s_waitcnt lgkmcnt(3)
	s_waitcnt lgkmcnt(2)
	ds_read2_b32 v[50:51], v9 offset0:198 offset1:206
	ds_read2_b32 v[52:53], v9 offset0:231 offset1:239
	v_cvt_pk_bf16_f32 v33, v42, v44
	s_waitcnt lgkmcnt(3)
	s_waitcnt lgkmcnt(2)
	v_cvt_pk_bf16_f32 v34, v46, v48
	s_waitcnt lgkmcnt(1)
	s_waitcnt lgkmcnt(0)
	v_cvt_pk_bf16_f32 v35, v50, v52
	v_or_b32_e32 v5, s26, v1
	v_lshlrev_b32_e32 v54, 14, v5
	v_mov_b32_e32 v55, v3
	v_lshl_add_u64 v[54:55], v[38:39], 0, v[54:55]
	global_store_dwordx4 v[54:55], v[32:35], off
	s_nop 1
	v_cvt_pk_bf16_f32 v32, v37, v41
	v_cvt_pk_bf16_f32 v33, v43, v45
	v_cvt_pk_bf16_f32 v34, v47, v49
	v_cvt_pk_bf16_f32 v35, v51, v53
	v_or_b32_e32 v5, s26, v6
	v_lshlrev_b32_e32 v36, 14, v5
	v_mov_b32_e32 v37, v3
	ds_read2_b32 v[40:41], v9 offset0:16 offset1:24
	v_lshl_add_u64 v[36:37], v[38:39], 0, v[36:37]
	global_store_dwordx4 v[36:37], v[32:35], off
	ds_read2_b32 v[36:37], v9 offset0:49 offset1:57
	ds_read2_b32 v[42:43], v9 offset0:82 offset1:90
	ds_read2_b32 v[44:45], v9 offset0:115 offset1:123
	s_waitcnt lgkmcnt(3)
	s_waitcnt lgkmcnt(2)
	ds_read2_b32 v[46:47], v9 offset0:148 offset1:156
	ds_read2_b32 v[48:49], v9 offset0:181 offset1:189
	v_cvt_pk_bf16_f32 v32, v40, v36
	s_waitcnt lgkmcnt(3)
	s_waitcnt lgkmcnt(2)
	ds_read2_b32 v[50:51], v9 offset0:214 offset1:222
	ds_read2_b32 v[52:53], v9 offset0:247 offset1:255
	v_cvt_pk_bf16_f32 v33, v42, v44
	s_waitcnt lgkmcnt(3)
	s_waitcnt lgkmcnt(2)
	v_cvt_pk_bf16_f32 v34, v46, v48
	s_waitcnt lgkmcnt(1)
	s_waitcnt lgkmcnt(0)
	v_cvt_pk_bf16_f32 v35, v50, v52
	v_or_b32_e32 v5, s26, v7
	v_lshlrev_b32_e32 v54, 14, v5
	v_mov_b32_e32 v55, v3
	v_lshl_add_u64 v[54:55], v[38:39], 0, v[54:55]
	global_store_dwordx4 v[54:55], v[32:35], off
	s_nop 1
	v_cvt_pk_bf16_f32 v32, v41, v37
	v_cvt_pk_bf16_f32 v33, v43, v45
	v_cvt_pk_bf16_f32 v34, v47, v49
	v_cvt_pk_bf16_f32 v35, v51, v53
	v_or_b32_e32 v5, s26, v8
	v_lshlrev_b32_e32 v36, 14, v5
	v_mov_b32_e32 v37, v3
	v_lshl_add_u64 v[36:37], v[38:39], 0, v[36:37]
	global_store_dwordx4 v[36:37], v[32:35], off
	s_waitcnt lgkmcnt(0)
	s_mov_b64 s[26:27], 0
.LBB0_34:
	s_andn2_b64 vcc, exec, s[26:27]
	s_cbranch_vccnz .LBB0_36
	s_add_u32 s26, s4, s24
	s_addc_u32 s25, s5, s25
	s_add_i32 s24, s61, 0xe400
	s_bfe_u32 s64, s24, 0x80008
	s_and_b32 s24, s31, 0x1fe0
	s_lshl_b32 s27, s24, 2
	s_add_u32 s26, s26, s27
	v_lshl_or_b32 v5, s64, 6, v1
	s_addc_u32 s27, s25, 0
	v_lshl_add_u64 v[32:33], s[26:27], 0, v[2:3]
	v_lshlrev_b32_e32 v34, 15, v5
	v_mov_b32_e32 v35, v3
	v_lshl_add_u64 v[56:57], v[32:33], 0, v[34:35]
	v_add_co_u32_e32 v36, vcc, s38, v56
	s_nop 1
	v_addc_co_u32_e32 v37, vcc, 0, v57, vcc
	v_add_co_u32_e32 v40, vcc, s44, v56
	global_load_dwordx4 v[32:35], v[56:57], off
	s_nop 0
	global_load_dwordx4 v[36:39], v[36:37], off
	v_addc_co_u32_e32 v41, vcc, 0, v57, vcc
	v_add_co_u32_e32 v44, vcc, s45, v56
	s_nop 1
	v_addc_co_u32_e32 v45, vcc, 0, v57, vcc
	v_add_co_u32_e32 v48, vcc, s46, v56
	global_load_dwordx4 v[40:43], v[40:41], off
	s_nop 0
	global_load_dwordx4 v[44:47], v[44:45], off
	v_addc_co_u32_e32 v49, vcc, 0, v57, vcc
	v_add_co_u32_e32 v52, vcc, s47, v56
	s_nop 1
	v_addc_co_u32_e32 v53, vcc, 0, v57, vcc
	v_add_co_u32_e32 v58, vcc, s48, v56
	global_load_dwordx4 v[48:51], v[48:49], off
	s_nop 0
	global_load_dwordx4 v[52:55], v[52:53], off
	v_addc_co_u32_e32 v59, vcc, 0, v57, vcc
	v_add_co_u32_e32 v60, vcc, s49, v56
	s_nop 1
	v_addc_co_u32_e32 v61, vcc, 0, v57, vcc
	global_load_dwordx4 v[56:59], v[58:59], off
	s_nop 0
	global_load_dwordx4 v[60:63], v[60:61], off
	s_waitcnt vmcnt(7)
	ds_write2_b32 v10, v32, v33 offset1:1
	ds_write2_b32 v10, v34, v35 offset0:2 offset1:3
	s_waitcnt vmcnt(6)
	ds_write2_b32 v11, v36, v37 offset1:1
	ds_write2_b32 v12, v38, v39 offset1:1
	s_waitcnt vmcnt(5)
	ds_write2_b32 v13, v40, v41 offset1:1
	ds_write2_b32 v14, v42, v43 offset1:1
	s_waitcnt vmcnt(4)
	ds_write2_b32 v15, v44, v45 offset1:1
	ds_write2_b32 v16, v46, v47 offset1:1
	s_waitcnt vmcnt(3)
	ds_write2_b32 v17, v48, v49 offset1:1
	ds_write2_b32 v18, v50, v51 offset1:1
	s_waitcnt vmcnt(2)
	ds_write2_b32 v19, v52, v53 offset1:1
	ds_write2_b32 v20, v54, v55 offset1:1
	s_waitcnt vmcnt(1)
	ds_write2_b32 v21, v56, v57 offset1:1
	ds_write2_b32 v22, v58, v59 offset1:1
	s_waitcnt vmcnt(0)
	ds_write2_b32 v23, v60, v61 offset1:1
	ds_write2_b32 v24, v62, v63 offset1:1
	s_waitcnt lgkmcnt(0)
	ds_read2_b32 v[36:37], v9 offset1:8
	ds_read2_b32 v[40:41], v9 offset0:33 offset1:41
	s_lshl_b32 s25, s64, 7
	s_add_u32 s26, s62, s25
	ds_read2_b32 v[42:43], v9 offset0:66 offset1:74
	s_addc_u32 s27, s63, 0
	v_mov_b32_e32 v5, v3
	ds_read2_b32 v[44:45], v9 offset0:99 offset1:107
	v_lshl_add_u64 v[32:33], s[26:27], 0, v[4:5]
	s_waitcnt lgkmcnt(3)
	v_lshl_add_u64 v[38:39], v[32:33], 0, s[18:19]
	s_waitcnt lgkmcnt(2)
	ds_read2_b32 v[46:47], v9 offset0:132 offset1:140
	ds_read2_b32 v[48:49], v9 offset0:165 offset1:173
	v_cvt_pk_bf16_f32 v32, v36, v40
	s_waitcnt lgkmcnt(3)
	s_waitcnt lgkmcnt(2)
	ds_read2_b32 v[50:51], v9 offset0:198 offset1:206
	ds_read2_b32 v[52:53], v9 offset0:231 offset1:239
	v_cvt_pk_bf16_f32 v33, v42, v44
	s_waitcnt lgkmcnt(3)
	s_waitcnt lgkmcnt(2)
	v_cvt_pk_bf16_f32 v34, v46, v48
	s_waitcnt lgkmcnt(1)
	s_waitcnt lgkmcnt(0)
	v_cvt_pk_bf16_f32 v35, v50, v52
	v_or_b32_e32 v5, s24, v1
	v_lshlrev_b32_e32 v54, 12, v5
	v_mov_b32_e32 v55, v3
	v_lshl_add_u64 v[54:55], v[38:39], 0, v[54:55]
	global_store_dwordx4 v[54:55], v[32:35], off
	s_nop 1
	v_cvt_pk_bf16_f32 v32, v37, v41
	v_cvt_pk_bf16_f32 v33, v43, v45
	v_cvt_pk_bf16_f32 v34, v47, v49
	v_cvt_pk_bf16_f32 v35, v51, v53
	v_or_b32_e32 v5, s24, v6
	v_lshlrev_b32_e32 v36, 12, v5
	v_mov_b32_e32 v37, v3
	ds_read2_b32 v[40:41], v9 offset0:16 offset1:24
	v_lshl_add_u64 v[36:37], v[38:39], 0, v[36:37]
	global_store_dwordx4 v[36:37], v[32:35], off
	ds_read2_b32 v[36:37], v9 offset0:49 offset1:57
	ds_read2_b32 v[42:43], v9 offset0:82 offset1:90
	ds_read2_b32 v[44:45], v9 offset0:115 offset1:123
	s_waitcnt lgkmcnt(3)
	s_waitcnt lgkmcnt(2)
	ds_read2_b32 v[46:47], v9 offset0:148 offset1:156
	ds_read2_b32 v[48:49], v9 offset0:181 offset1:189
	v_cvt_pk_bf16_f32 v32, v40, v36
	s_waitcnt lgkmcnt(3)
	s_waitcnt lgkmcnt(2)
	ds_read2_b32 v[50:51], v9 offset0:214 offset1:222
	ds_read2_b32 v[52:53], v9 offset0:247 offset1:255
	v_cvt_pk_bf16_f32 v33, v42, v44
	s_waitcnt lgkmcnt(3)
	s_waitcnt lgkmcnt(2)
	v_cvt_pk_bf16_f32 v34, v46, v48
	s_waitcnt lgkmcnt(1)
	s_waitcnt lgkmcnt(0)
	v_cvt_pk_bf16_f32 v35, v50, v52
	v_or_b32_e32 v5, s24, v7
	v_lshlrev_b32_e32 v54, 12, v5
	v_mov_b32_e32 v55, v3
	v_lshl_add_u64 v[54:55], v[38:39], 0, v[54:55]
	global_store_dwordx4 v[54:55], v[32:35], off
	s_nop 1
	v_cvt_pk_bf16_f32 v32, v41, v37
	v_cvt_pk_bf16_f32 v33, v43, v45
	v_cvt_pk_bf16_f32 v34, v47, v49
	v_cvt_pk_bf16_f32 v35, v51, v53
	v_or_b32_e32 v5, s24, v8
	v_lshlrev_b32_e32 v36, 12, v5
	v_mov_b32_e32 v37, v3
	v_lshl_add_u64 v[36:37], v[38:39], 0, v[36:37]
	global_store_dwordx4 v[36:37], v[32:35], off
	s_waitcnt lgkmcnt(0)

.LBB0_37:
	s_andn2_b64 vcc, exec, s[24:25]
	s_cbranch_vccnz .LBB0_39
	s_lshl_b64 s[24:25], s[22:23], 24
	s_add_u32 s24, s2, s24
	s_addc_u32 s25, s3, s25
	s_add_i32 s23, s61, 0xec00
	s_and_b32 s26, s23, 0xffc0
	s_and_b32 s23, s31, 0x7e0
	s_lshl_b32 s27, s23, 2
	s_add_u32 s24, s24, s27
	v_or_b32_e32 v5, s26, v1
	s_addc_u32 s25, s25, 0
	v_lshl_add_u64 v[32:33], s[24:25], 0, v[2:3]
	v_lshlrev_b32_e32 v34, 13, v5
	v_mov_b32_e32 v35, v3
	v_lshl_add_u64 v[56:57], v[32:33], 0, v[34:35]
	v_add_co_u32_e32 v36, vcc, s35, v56
	s_nop 1
	v_addc_co_u32_e32 v37, vcc, 0, v57, vcc
	v_add_co_u32_e32 v40, vcc, s36, v56
	global_load_dwordx4 v[32:35], v[56:57], off
	s_nop 0
	global_load_dwordx4 v[36:39], v[36:37], off
	v_addc_co_u32_e32 v41, vcc, 0, v57, vcc
	v_add_co_u32_e32 v44, vcc, s37, v56
	s_nop 1
	v_addc_co_u32_e32 v45, vcc, 0, v57, vcc
	v_add_co_u32_e32 v48, vcc, s38, v56
	global_load_dwordx4 v[40:43], v[40:41], off
	s_nop 0
	global_load_dwordx4 v[44:47], v[44:45], off
	v_addc_co_u32_e32 v49, vcc, 0, v57, vcc
	v_add_co_u32_e32 v52, vcc, s39, v56
	s_nop 1
	v_addc_co_u32_e32 v53, vcc, 0, v57, vcc
	v_add_co_u32_e32 v58, vcc, s40, v56
	global_load_dwordx4 v[48:51], v[48:49], off
	s_nop 0
	global_load_dwordx4 v[52:55], v[52:53], off
	v_addc_co_u32_e32 v59, vcc, 0, v57, vcc
	v_add_co_u32_e32 v60, vcc, s41, v56
	s_nop 1
	v_addc_co_u32_e32 v61, vcc, 0, v57, vcc
	global_load_dwordx4 v[56:59], v[58:59], off
	s_nop 0
	global_load_dwordx4 v[60:63], v[60:61], off
	s_waitcnt vmcnt(7)
	ds_write2_b32 v10, v32, v33 offset1:1
	ds_write2_b32 v10, v34, v35 offset0:2 offset1:3
	s_waitcnt vmcnt(6)
	ds_write2_b32 v11, v36, v37 offset1:1
	ds_write2_b32 v12, v38, v39 offset1:1
	s_waitcnt vmcnt(5)
	ds_write2_b32 v13, v40, v41 offset1:1
	ds_write2_b32 v14, v42, v43 offset1:1
	s_waitcnt vmcnt(4)
	ds_write2_b32 v15, v44, v45 offset1:1
	ds_write2_b32 v16, v46, v47 offset1:1
	s_waitcnt vmcnt(3)
	ds_write2_b32 v17, v48, v49 offset1:1
	ds_write2_b32 v18, v50, v51 offset1:1
	s_waitcnt vmcnt(2)
	ds_write2_b32 v19, v52, v53 offset1:1
	ds_write2_b32 v20, v54, v55 offset1:1
	s_waitcnt vmcnt(1)
	ds_write2_b32 v21, v56, v57 offset1:1
	ds_write2_b32 v22, v58, v59 offset1:1
	s_waitcnt vmcnt(0)
	ds_write2_b32 v23, v60, v61 offset1:1
	ds_write2_b32 v24, v62, v63 offset1:1
	s_waitcnt lgkmcnt(0)
	ds_read2_b32 v[36:37], v9 offset1:8
	ds_read2_b32 v[40:41], v9 offset0:33 offset1:41
	s_lshl_b32 s24, s26, 1
	s_add_u32 s24, s62, s24
	ds_read2_b32 v[42:43], v9 offset0:66 offset1:74
	s_addc_u32 s25, s63, 0
	v_mov_b32_e32 v5, v3
	ds_read2_b32 v[44:45], v9 offset0:99 offset1:107
	v_lshl_add_u64 v[32:33], s[24:25], 0, v[4:5]
	s_waitcnt lgkmcnt(3)
	v_lshl_add_u64 v[38:39], v[32:33], 0, s[20:21]
	s_waitcnt lgkmcnt(2)
	ds_read2_b32 v[46:47], v9 offset0:132 offset1:140
	ds_read2_b32 v[48:49], v9 offset0:165 offset1:173
	v_cvt_pk_bf16_f32 v32, v36, v40
	s_waitcnt lgkmcnt(3)
	s_waitcnt lgkmcnt(2)
	ds_read2_b32 v[50:51], v9 offset0:198 offset1:206
	ds_read2_b32 v[52:53], v9 offset0:231 offset1:239
	v_cvt_pk_bf16_f32 v33, v42, v44
	s_waitcnt lgkmcnt(3)
	s_waitcnt lgkmcnt(2)
	v_cvt_pk_bf16_f32 v34, v46, v48
	s_waitcnt lgkmcnt(1)
	s_waitcnt lgkmcnt(0)
	v_cvt_pk_bf16_f32 v35, v50, v52
	v_or_b32_e32 v5, s23, v1
	v_lshlrev_b32_e32 v54, 12, v5
	v_mov_b32_e32 v55, v3
	v_lshl_add_u64 v[54:55], v[38:39], 0, v[54:55]
	global_store_dwordx4 v[54:55], v[32:35], off
	s_nop 1
	v_cvt_pk_bf16_f32 v32, v37, v41
	v_cvt_pk_bf16_f32 v33, v43, v45
	v_cvt_pk_bf16_f32 v34, v47, v49
	v_cvt_pk_bf16_f32 v35, v51, v53
	v_or_b32_e32 v5, s23, v6
	v_lshlrev_b32_e32 v36, 12, v5
	v_mov_b32_e32 v37, v3
	ds_read2_b32 v[40:41], v9 offset0:16 offset1:24
	v_lshl_add_u64 v[36:37], v[38:39], 0, v[36:37]
	global_store_dwordx4 v[36:37], v[32:35], off
	ds_read2_b32 v[36:37], v9 offset0:49 offset1:57
	ds_read2_b32 v[42:43], v9 offset0:82 offset1:90
	ds_read2_b32 v[44:45], v9 offset0:115 offset1:123
	s_waitcnt lgkmcnt(3)
	s_waitcnt lgkmcnt(2)
	ds_read2_b32 v[46:47], v9 offset0:148 offset1:156
	ds_read2_b32 v[48:49], v9 offset0:181 offset1:189
	v_cvt_pk_bf16_f32 v32, v40, v36
	s_waitcnt lgkmcnt(3)
	s_waitcnt lgkmcnt(2)
	ds_read2_b32 v[50:51], v9 offset0:214 offset1:222
	ds_read2_b32 v[52:53], v9 offset0:247 offset1:255
	v_cvt_pk_bf16_f32 v33, v42, v44
	s_waitcnt lgkmcnt(3)
	s_waitcnt lgkmcnt(2)
	v_cvt_pk_bf16_f32 v34, v46, v48
	s_waitcnt lgkmcnt(1)
	s_waitcnt lgkmcnt(0)
	v_cvt_pk_bf16_f32 v35, v50, v52
	v_or_b32_e32 v5, s23, v7
	v_lshlrev_b32_e32 v54, 12, v5
	v_mov_b32_e32 v55, v3
	v_lshl_add_u64 v[54:55], v[38:39], 0, v[54:55]
	global_store_dwordx4 v[54:55], v[32:35], off
	s_nop 1
	v_cvt_pk_bf16_f32 v32, v41, v37
	v_cvt_pk_bf16_f32 v33, v43, v45
	v_cvt_pk_bf16_f32 v34, v47, v49
	v_cvt_pk_bf16_f32 v35, v51, v53
	v_or_b32_e32 v5, s23, v8
	v_lshlrev_b32_e32 v36, 12, v5
	v_mov_b32_e32 v37, v3
	v_lshl_add_u64 v[36:37], v[38:39], 0, v[36:37]
	global_store_dwordx4 v[36:37], v[32:35], off
	s_waitcnt lgkmcnt(0)

.LBB0_40:
	s_andn2_b64 vcc, exec, s[24:25]
	s_cbranch_vccnz .LBB0_42
	s_mul_i32 s24, s22, 0x5d00000
	s_mul_hi_i32 s23, s22, 0x5d00000
	s_add_u32 s26, s29, s24
	s_addc_u32 s23, s30, s23
	s_add_i32 s24, s61, 0xf200
	s_and_b32 s25, s24, 0xffff
	s_mul_i32 s25, s25, 0xaaab
	s_lshr_b32 s27, s25, 21
	s_mul_i32 s25, s27, 48
	s_sub_i32 s24, s24, s25
	s_lshl_b32 s62, s24, 5
	s_lshl_b32 s24, s24, 7
	s_and_b32 s24, s24, 0x3ff80
	s_add_u32 s24, s59, s24
	v_lshl_or_b32 v5, s27, 6, v1
	s_addc_u32 s25, s60, 0
	v_lshl_add_u64 v[32:33], s[24:25], 0, v[2:3]
	v_mul_u32_u24_e32 v34, 0x5040, v5
	v_mov_b32_e32 v35, v3
	v_lshl_add_u64 v[56:57], v[32:33], 0, v[34:35]
	v_add_co_u32_e32 v32, vcc, s51, v56
	s_nop 1
	v_addc_co_u32_e32 v33, vcc, 0, v57, vcc
	v_add_co_u32_e32 v36, vcc, s52, v56
	s_nop 1
	v_addc_co_u32_e32 v37, vcc, 0, v57, vcc
	v_add_co_u32_e32 v40, vcc, s53, v56
	global_load_dwordx4 v[32:35], v[32:33], off offset:2112
	s_nop 0
	global_load_dwordx4 v[36:39], v[36:37], off offset:2624
	v_addc_co_u32_e32 v41, vcc, 0, v57, vcc
	v_add_co_u32_e32 v44, vcc, s54, v56
	s_nop 1
	v_addc_co_u32_e32 v45, vcc, 0, v57, vcc
	v_add_co_u32_e32 v48, vcc, s55, v56
	global_load_dwordx4 v[40:43], v[40:41], off offset:3136
	s_nop 0
	global_load_dwordx4 v[44:47], v[44:45], off offset:3648
	v_addc_co_u32_e32 v49, vcc, 0, v57, vcc
	v_add_co_u32_e32 v52, vcc, s56, v56
	s_nop 1
	v_addc_co_u32_e32 v53, vcc, 0, v57, vcc
	v_add_co_u32_e32 v58, vcc, s57, v56
	global_load_dwordx4 v[48:51], v[48:49], off offset:64
	s_nop 0
	global_load_dwordx4 v[52:55], v[52:53], off offset:576
	v_addc_co_u32_e32 v59, vcc, 0, v57, vcc
	v_add_co_u32_e32 v60, vcc, s58, v56
	s_nop 1
	v_addc_co_u32_e32 v61, vcc, 0, v57, vcc
	global_load_dwordx4 v[56:59], v[58:59], off offset:1088
	s_nop 0
	global_load_dwordx4 v[60:63], v[60:61], off offset:1600
	s_waitcnt vmcnt(7)
	ds_write2_b32 v10, v32, v33 offset1:1
	ds_write2_b32 v10, v34, v35 offset0:2 offset1:3
	s_waitcnt vmcnt(6)
	ds_write2_b32 v11, v36, v37 offset1:1
	ds_write2_b32 v12, v38, v39 offset1:1
	s_waitcnt vmcnt(5)
	ds_write2_b32 v13, v40, v41 offset1:1
	ds_write2_b32 v14, v42, v43 offset1:1
	s_waitcnt vmcnt(4)
	ds_write2_b32 v15, v44, v45 offset1:1
	ds_write2_b32 v16, v46, v47 offset1:1
	s_waitcnt vmcnt(3)
	ds_write2_b32 v17, v48, v49 offset1:1
	ds_write2_b32 v18, v50, v51 offset1:1
	s_waitcnt vmcnt(2)
	ds_write2_b32 v19, v52, v53 offset1:1
	ds_write2_b32 v20, v54, v55 offset1:1
	s_waitcnt vmcnt(1)
	ds_write2_b32 v21, v56, v57 offset1:1
	ds_write2_b32 v22, v58, v59 offset1:1
	s_waitcnt vmcnt(0)
	ds_write2_b32 v23, v60, v61 offset1:1
	ds_write2_b32 v24, v62, v63 offset1:1
	s_waitcnt lgkmcnt(0)
	ds_read2_b32 v[36:37], v9 offset1:8
	s_addk_i32 s62, 0xe00
	ds_read2_b32 v[40:41], v9 offset0:33 offset1:41
	s_and_b32 s62, s62, 0xffe0
	s_lshl_b32 s24, s27, 7
	s_add_u32 s24, s26, s24
	ds_read2_b32 v[42:43], v9 offset0:66 offset1:74
	s_addc_u32 s25, s23, 0
	v_mov_b32_e32 v5, v3
	ds_read2_b32 v[44:45], v9 offset0:99 offset1:107
	v_lshl_add_u64 v[38:39], s[24:25], 0, v[4:5]
	s_waitcnt lgkmcnt(3)
	s_waitcnt lgkmcnt(2)
	ds_read2_b32 v[46:47], v9 offset0:132 offset1:140
	ds_read2_b32 v[48:49], v9 offset0:165 offset1:173
	v_cvt_pk_bf16_f32 v32, v36, v40
	s_waitcnt lgkmcnt(3)
	s_waitcnt lgkmcnt(2)
	ds_read2_b32 v[50:51], v9 offset0:198 offset1:206
	ds_read2_b32 v[52:53], v9 offset0:231 offset1:239
	v_cvt_pk_bf16_f32 v33, v42, v44
	s_waitcnt lgkmcnt(3)
	s_waitcnt lgkmcnt(2)
	v_cvt_pk_bf16_f32 v34, v46, v48
	s_waitcnt lgkmcnt(1)
	s_waitcnt lgkmcnt(0)
	v_cvt_pk_bf16_f32 v35, v50, v52
	v_or_b32_e32 v5, s62, v1
	v_lshlrev_b32_e32 v54, 12, v5
	v_mov_b32_e32 v55, v3
	v_lshl_add_u64 v[54:55], v[38:39], 0, v[54:55]
	global_store_dwordx4 v[54:55], v[32:35], off
	s_nop 1
	v_cvt_pk_bf16_f32 v32, v37, v41
	v_cvt_pk_bf16_f32 v33, v43, v45
	v_cvt_pk_bf16_f32 v34, v47, v49
	v_cvt_pk_bf16_f32 v35, v51, v53
	v_or_b32_e32 v5, s62, v6
	v_lshlrev_b32_e32 v36, 12, v5
	v_mov_b32_e32 v37, v3
	ds_read2_b32 v[40:41], v9 offset0:16 offset1:24
	v_lshl_add_u64 v[36:37], v[38:39], 0, v[36:37]
	global_store_dwordx4 v[36:37], v[32:35], off
	ds_read2_b32 v[36:37], v9 offset0:49 offset1:57
	ds_read2_b32 v[42:43], v9 offset0:82 offset1:90
	ds_read2_b32 v[44:45], v9 offset0:115 offset1:123
	s_waitcnt lgkmcnt(3)
	s_waitcnt lgkmcnt(2)
	ds_read2_b32 v[46:47], v9 offset0:148 offset1:156
	ds_read2_b32 v[48:49], v9 offset0:181 offset1:189
	v_cvt_pk_bf16_f32 v32, v40, v36
	s_waitcnt lgkmcnt(3)
	s_waitcnt lgkmcnt(2)
	ds_read2_b32 v[50:51], v9 offset0:214 offset1:222
	ds_read2_b32 v[52:53], v9 offset0:247 offset1:255
	v_cvt_pk_bf16_f32 v33, v42, v44
	s_waitcnt lgkmcnt(3)
	s_waitcnt lgkmcnt(2)
	v_cvt_pk_bf16_f32 v34, v46, v48
	s_waitcnt lgkmcnt(1)
	s_waitcnt lgkmcnt(0)
	v_cvt_pk_bf16_f32 v35, v50, v52
	v_or_b32_e32 v5, s62, v7
	v_lshlrev_b32_e32 v54, 12, v5
	v_mov_b32_e32 v55, v3
	v_lshl_add_u64 v[54:55], v[38:39], 0, v[54:55]
	global_store_dwordx4 v[54:55], v[32:35], off
	s_nop 1
	v_cvt_pk_bf16_f32 v32, v41, v37
	v_cvt_pk_bf16_f32 v33, v43, v45
	v_cvt_pk_bf16_f32 v34, v47, v49
	v_cvt_pk_bf16_f32 v35, v51, v53
	v_or_b32_e32 v5, s62, v8
	v_lshlrev_b32_e32 v36, 12, v5
	v_mov_b32_e32 v37, v3
	v_lshl_add_u64 v[36:37], v[38:39], 0, v[36:37]
	global_store_dwordx4 v[36:37], v[32:35], off
	s_waitcnt lgkmcnt(0)

.LBB0_43:
	s_mul_hi_i32 s23, s22, 0x5d00000
	s_mul_i32 s22, s22, 0x5d00000
	s_add_u32 s62, s29, s22
	s_mul_i32 s22, s61, 0x4925
	s_addc_u32 s63, s30, s23
	s_lshr_b32 s23, s22, 31
	s_ashr_i32 s22, s22, 21
	s_add_i32 s22, s22, s23
	s_sext_i32_i16 s23, s22
	s_mulk_i32 s22, 0x70
	s_sub_i32 s22, s61, s22
	s_sext_i32_i16 s22, s22
	s_lshl_b32 s22, s22, 5
	s_lshl_b32 s24, s23, 6
	s_ashr_i32 s23, s22, 31
	s_lshl_b64 s[26:27], s[22:23], 2
	v_or_b32_e32 v5, s24, v1
	s_add_u32 s26, s59, s26
	s_addc_u32 s27, s60, s27
	v_mul_i32_i24_e32 v32, 0x5040, v5
	v_mad_i32_i24 v34, v5, s50, v25
	v_mad_i32_i24 v40, v5, s50, v26
	v_mad_i32_i24 v42, v5, s50, v27
	v_mad_i32_i24 v48, v5, s50, v28
	v_mad_i32_i24 v50, v5, s50, v29
	v_mad_i32_i24 v58, v5, s50, v30
	v_mad_i32_i24 v60, v5, s50, v31
	v_lshl_add_u64 v[56:57], s[26:27], 0, v[2:3]
	v_ashrrev_i32_e32 v33, 31, v32
	v_ashrrev_i32_e32 v35, 31, v34
	v_ashrrev_i32_e32 v41, 31, v40
	v_ashrrev_i32_e32 v43, 31, v42
	v_ashrrev_i32_e32 v49, 31, v48
	v_ashrrev_i32_e32 v51, 31, v50
	v_ashrrev_i32_e32 v59, 31, v58
	v_ashrrev_i32_e32 v61, 31, v60
	v_lshl_add_u64 v[32:33], v[56:57], 0, v[32:33]
	v_lshl_add_u64 v[36:37], v[56:57], 0, v[34:35]
	v_lshl_add_u64 v[40:41], v[56:57], 0, v[40:41]
	v_lshl_add_u64 v[44:45], v[56:57], 0, v[42:43]
	v_lshl_add_u64 v[48:49], v[56:57], 0, v[48:49]
	v_lshl_add_u64 v[52:53], v[56:57], 0, v[50:51]
	v_lshl_add_u64 v[58:59], v[56:57], 0, v[58:59]
	v_lshl_add_u64 v[60:61], v[56:57], 0, v[60:61]
	global_load_dwordx4 v[32:35], v[32:33], off
	s_nop 0
	global_load_dwordx4 v[36:39], v[36:37], off
	s_nop 0
	global_load_dwordx4 v[40:43], v[40:41], off
	s_nop 0
	global_load_dwordx4 v[44:47], v[44:45], off
	s_nop 0
	global_load_dwordx4 v[48:51], v[48:49], off
	s_nop 0
	global_load_dwordx4 v[52:55], v[52:53], off
	s_nop 0
	global_load_dwordx4 v[56:59], v[58:59], off
	s_nop 0
	global_load_dwordx4 v[60:63], v[60:61], off
	s_waitcnt vmcnt(7)
	ds_write2_b32 v10, v32, v33 offset1:1
	ds_write2_b32 v10, v34, v35 offset0:2 offset1:3
	s_waitcnt vmcnt(6)
	ds_write2_b32 v11, v36, v37 offset1:1
	ds_write2_b32 v12, v38, v39 offset1:1
	s_waitcnt vmcnt(5)
	ds_write2_b32 v13, v40, v41 offset1:1
	ds_write2_b32 v14, v42, v43 offset1:1
	s_waitcnt vmcnt(4)
	ds_write2_b32 v15, v44, v45 offset1:1
	ds_write2_b32 v16, v46, v47 offset1:1
	s_waitcnt vmcnt(3)
	ds_write2_b32 v17, v48, v49 offset1:1
	ds_write2_b32 v18, v50, v51 offset1:1
	s_waitcnt vmcnt(2)
	ds_write2_b32 v19, v52, v53 offset1:1
	ds_write2_b32 v20, v54, v55 offset1:1
	s_waitcnt vmcnt(1)
	ds_write2_b32 v21, v56, v57 offset1:1
	ds_write2_b32 v22, v58, v59 offset1:1
	s_waitcnt vmcnt(0)
	ds_write2_b32 v23, v60, v61 offset1:1
	ds_write2_b32 v24, v62, v63 offset1:1
	s_waitcnt lgkmcnt(0)
	ds_read2_b32 v[36:37], v9 offset1:8
	s_ashr_i32 s25, s24, 31
	ds_read2_b32 v[40:41], v9 offset0:33 offset1:41
	s_lshl_b64 s[24:25], s[24:25], 1
	s_add_u32 s24, s62, s24
	ds_read2_b32 v[42:43], v9 offset0:66 offset1:74
	s_addc_u32 s25, s63, s25
	v_mov_b32_e32 v5, v3
	ds_read2_b32 v[44:45], v9 offset0:99 offset1:107
	v_lshl_add_u64 v[38:39], s[24:25], 0, v[4:5]
	s_waitcnt lgkmcnt(3)
	s_waitcnt lgkmcnt(2)
	ds_read2_b32 v[46:47], v9 offset0:132 offset1:140
	ds_read2_b32 v[48:49], v9 offset0:165 offset1:173
	v_cvt_pk_bf16_f32 v32, v36, v40
	s_waitcnt lgkmcnt(3)
	s_waitcnt lgkmcnt(2)
	ds_read2_b32 v[50:51], v9 offset0:198 offset1:206
	ds_read2_b32 v[52:53], v9 offset0:231 offset1:239
	v_cvt_pk_bf16_f32 v33, v42, v44
	s_waitcnt lgkmcnt(3)
	s_waitcnt lgkmcnt(2)
	v_cvt_pk_bf16_f32 v34, v46, v48
	s_waitcnt lgkmcnt(1)
	v_or_b32_e32 v54, s22, v1
	s_waitcnt lgkmcnt(0)
	v_ashrrev_i32_e32 v55, 31, v54
	v_lshlrev_b64 v[54:55], 12, v[54:55]
	v_cvt_pk_bf16_f32 v35, v50, v52
	v_lshl_add_u64 v[54:55], v[38:39], 0, v[54:55]
	global_store_dwordx4 v[54:55], v[32:35], off
	s_nop 1
	v_cvt_pk_bf16_f32 v32, v37, v41
	v_cvt_pk_bf16_f32 v33, v43, v45
	v_cvt_pk_bf16_f32 v34, v47, v49
	v_or_b32_e32 v36, s22, v6
	v_ashrrev_i32_e32 v37, 31, v36
	v_lshlrev_b64 v[36:37], 12, v[36:37]
	v_cvt_pk_bf16_f32 v35, v51, v53
	ds_read2_b32 v[40:41], v9 offset0:16 offset1:24
	v_lshl_add_u64 v[36:37], v[38:39], 0, v[36:37]
	global_store_dwordx4 v[36:37], v[32:35], off
	ds_read2_b32 v[36:37], v9 offset0:49 offset1:57
	ds_read2_b32 v[42:43], v9 offset0:82 offset1:90
	ds_read2_b32 v[44:45], v9 offset0:115 offset1:123
	s_waitcnt lgkmcnt(3)
	s_waitcnt lgkmcnt(2)
	ds_read2_b32 v[46:47], v9 offset0:148 offset1:156
	ds_read2_b32 v[48:49], v9 offset0:181 offset1:189
	v_cvt_pk_bf16_f32 v32, v40, v36
	s_waitcnt lgkmcnt(3)
	s_waitcnt lgkmcnt(2)
	ds_read2_b32 v[50:51], v9 offset0:214 offset1:222
	ds_read2_b32 v[52:53], v9 offset0:247 offset1:255
	v_cvt_pk_bf16_f32 v33, v42, v44
	s_waitcnt lgkmcnt(3)
	s_waitcnt lgkmcnt(2)
	v_cvt_pk_bf16_f32 v34, v46, v48
	s_waitcnt lgkmcnt(1)
	v_or_b32_e32 v54, s22, v7
	s_waitcnt lgkmcnt(0)
	v_ashrrev_i32_e32 v55, 31, v54
	v_lshlrev_b64 v[54:55], 12, v[54:55]
	v_cvt_pk_bf16_f32 v35, v50, v52
	v_lshl_add_u64 v[54:55], v[38:39], 0, v[54:55]
	global_store_dwordx4 v[54:55], v[32:35], off
	s_nop 1
	v_cvt_pk_bf16_f32 v32, v41, v37
	v_cvt_pk_bf16_f32 v33, v43, v45
	v_cvt_pk_bf16_f32 v34, v47, v49
	v_bfe_u32 v5, v51, 16, 1
	v_or_b32_e32 v36, s22, v8
	v_add3_u32 v5, v51, v5, s42
	v_bfe_u32 v35, v53, 16, 1
	v_ashrrev_i32_e32 v37, 31, v36
	v_lshrrev_b32_e32 v5, 16, v5
	v_add3_u32 v35, v53, v35, s42
	v_lshlrev_b64 v[36:37], 12, v[36:37]
	v_and_or_b32 v35, v35, s43, v5
	v_lshl_add_u64 v[36:37], v[38:39], 0, v[36:37]
	global_store_dwordx4 v[36:37], v[32:35], off
	s_waitcnt lgkmcnt(0)
	s_branch .LBB0_27

.LBB0_46:
	v_ashrrev_i32_e32 v9, 12, v1
	v_bfe_u32 v18, v1, 8, 4
	v_and_b32_e32 v19, 0x7f8, v8
	v_mad_i64_i32 v[10:11], s[16:17], v9, s6, v[2:3]
	v_lshlrev_b32_e32 v4, 2, v18
	v_mad_u64_u32 v[10:11], s[16:17], v19, s7, v[10:11]
	v_lshl_add_u64 v[10:11], v[10:11], 0, v[4:5]
	v_add_co_u32_e32 v12, vcc, 0x3000, v10
	v_lshlrev_b32_e32 v4, 12, v18
	s_nop 0
	v_addc_co_u32_e32 v13, vcc, 0, v11, vcc
	v_add_co_u32_e32 v14, vcc, 0x8000, v10
	v_add_u32_e32 v1, s4, v1
	s_nop 0
	v_addc_co_u32_e32 v15, vcc, 0, v11, vcc
	v_add_co_u32_e32 v16, vcc, 0xd000, v10
	global_load_dword v20, v[12:13], off offset:2048
	global_load_dword v21, v[14:15], off offset:2112
	v_addc_co_u32_e32 v17, vcc, 0, v11, vcc
	v_add_co_u32_e32 v12, vcc, 0x12000, v10
	v_add_u32_e32 v8, s5, v8
	s_nop 0
	v_addc_co_u32_e32 v13, vcc, 0, v11, vcc
	v_add_co_u32_e32 v14, vcc, 0x17000, v10
	global_load_dword v22, v[16:17], off offset:2176
	global_load_dword v23, v[12:13], off offset:2240
	v_addc_co_u32_e32 v15, vcc, 0, v11, vcc
	v_add_co_u32_e32 v12, vcc, 0x1c000, v10
	s_nop 1
	v_addc_co_u32_e32 v13, vcc, 0, v11, vcc
	v_add_co_u32_e32 v16, vcc, 0x21000, v10
	global_load_dword v24, v[14:15], off offset:2304
	global_load_dword v25, v[12:13], off offset:2368
	v_addc_co_u32_e32 v17, vcc, 0, v11, vcc
	v_add_co_u32_e32 v10, vcc, 0x26000, v10
	global_load_dword v13, v[16:17], off offset:2432
	s_nop 0
	v_addc_co_u32_e32 v11, vcc, 0, v11, vcc
	global_load_dword v16, v[10:11], off offset:2496
	v_mad_i64_i32 v[10:11], s[16:17], v9, s14, v[6:7]
	v_lshl_add_u64 v[10:11], v[10:11], 0, v[4:5]
	v_lshlrev_b32_e32 v4, 1, v19
	v_cmp_lt_i32_e32 vcc, s15, v1
	v_lshl_add_u64 v[10:11], v[10:11], 0, v[4:5]
	s_or_b64 s[2:3], vcc, s[2:3]
	v_add_co_u32_e32 v14, vcc, 0x1800000, v10
	s_waitcnt vmcnt(7)
	s_nop 0
	s_nop 0
	s_waitcnt vmcnt(6)
	v_addc_co_u32_e32 v15, vcc, 0, v11, vcc
	v_cvt_pk_bf16_f32 v10, v20, v21
	s_waitcnt vmcnt(5)
	s_waitcnt vmcnt(4)
	v_cvt_pk_bf16_f32 v11, v22, v23
	s_waitcnt vmcnt(3)
	s_waitcnt vmcnt(2)
	v_cvt_pk_bf16_f32 v12, v24, v25
	s_waitcnt vmcnt(1)
	v_bfe_u32 v17, v13, 16, 1
	v_add3_u32 v4, v13, v17, s12
	v_lshrrev_b32_e32 v4, 16, v4
	s_waitcnt vmcnt(0)
	v_bfe_u32 v9, v16, 16, 1
	v_add3_u32 v9, v16, v9, s12
	v_and_or_b32 v13, v9, s13, v4
	global_store_dwordx4 v[14:15], v[10:13], off
	s_andn2_b64 exec, exec, s[2:3]
	s_cbranch_execnz .LBB0_46

.LBB0_308:
	v_cvt_pk_bf16_f32 v28, v36, v37
	v_cvt_pk_bf16_f32 v29, v38, v39
	v_cvt_pk_bf16_f32 v30, v56, v57
	v_bfe_u32 v31, v58, 16, 1
	v_add3_u32 v31, v58, v31, s65
	v_bfe_u32 v32, v59, 16, 1
	v_lshrrev_b32_e32 v31, 16, v31
	v_add3_u32 v32, v59, v32, s65
	v_and_or_b32 v31, v32, s61, v31
	s_and_b64 vcc, exec, s[10:11]
	s_mov_b64 s[26:27], s[22:23]
	global_store_dwordx4 v40, v[28:31], s[20:21]
	s_cbranch_vccz .LBB0_310
	s_lshl_b64 s[26:27], s[14:15], 10
	v_lshl_add_u64 v[60:61], v[48:49], 0, s[26:27]
	s_or_b64 s[26:27], s[22:23], exec
	global_store_dwordx4 v[60:61], v[36:39], off

.LBB0_486:
	s_or_b64 exec, exec, s[0:1]
	v_sub_f32_e32 v37, v37, v38
	v_sub_f32_e32 v36, v36, v38
	v_mul_f32_e32 v37, 0x3fb8aa3b, v37
	v_mul_f32_e32 v36, 0x3fb8aa3b, v36
	v_exp_f32_e32 v37, v37
	v_exp_f32_e32 v36, v36
	v_and_b32_e32 v47, 0xffff0000, v1
	v_and_b32_e32 v46, 0xffff0000, v0
	v_mul_f32_e32 v37, 0x3db504f3, v37
	v_mul_f32_e32 v36, 0x3db504f3, v36
	ds_bpermute_b32 v38, v111, v37
	ds_bpermute_b32 v39, v111, v36
	ds_bpermute_b32 v40, v112, v37
	ds_bpermute_b32 v42, v113, v37
	ds_bpermute_b32 v37, v114, v37
	ds_bpermute_b32 v44, v114, v36
	ds_bpermute_b32 v41, v112, v36
	ds_bpermute_b32 v43, v113, v36
	s_waitcnt lgkmcnt(6)
	v_cndmask_b32_e64 v36, v39, v38, s[20:21]
	v_lshlrev_b32_e32 v39, 16, v1
	v_lshlrev_b32_e32 v38, 16, v0
	v_lshlrev_b32_e32 v49, 16, v3
	v_lshlrev_b32_e32 v48, 16, v2
	v_and_b32_e32 v51, 0xffff0000, v3
	v_and_b32_e32 v50, 0xffff0000, v2
	s_waitcnt lgkmcnt(2)
	v_cndmask_b32_e64 v44, v44, v37, s[20:21]
	v_pk_mul_f32 v[38:39], v[36:37], v[38:39] op_sel_hi:[0,1]
	v_pk_mul_f32 v[46:47], v[36:37], v[46:47] op_sel_hi:[0,1]
	v_pk_mul_f32 v[48:49], v[36:37], v[48:49] op_sel_hi:[0,1]
	v_pk_mul_f32 v[36:37], v[36:37], v[50:51] op_sel_hi:[0,1]
	s_waitcnt lgkmcnt(1)
	v_cndmask_b32_e64 v40, v41, v40, s[20:21]
	s_waitcnt lgkmcnt(0)
	v_cndmask_b32_e64 v42, v43, v42, s[20:21]
	v_bfe_u32 v41, v37, 16, 1
	s_nop 0
	v_bfe_u32 v45, v47, 16, 1
	v_bfe_u32 v50, v46, 16, 1
	v_add3_u32 v46, v46, v50, s65
	v_add3_u32 v45, v47, v45, s65
	v_add3_u32 v37, v37, v41, s65
	v_bfe_u32 v41, v38, 16, 1
	v_bfe_u32 v43, v39, 16, 1
	v_bfe_u32 v50, v49, 16, 1
	v_add3_u32 v49, v49, v50, s65
	v_add3_u32 v39, v39, v43, s65
	v_add3_u32 v38, v38, v41, s65
	v_lshrrev_b32_e32 v41, 16, v38
	v_lshrrev_b32_e32 v43, 16, v39
	v_lshrrev_b32_e32 v39, 16, v49
	v_and_or_b32 v39, v37, s61, v39
	v_cvt_pk_bf16_f32 v38, v48, v36
	v_and_or_b32 v37, v45, s61, v43
	v_and_or_b32 v36, v46, s61, v41
	s_barrier
	ds_write_b128 v135, v[36:39]
	ds_write_b128 v135, v[4:7] offset:32768
	v_lshlrev_b32_e32 v37, 16, v9
	v_lshlrev_b32_e32 v36, 16, v8
	v_and_b32_e32 v39, 0xffff0000, v9
	v_and_b32_e32 v38, 0xffff0000, v8
	v_lshlrev_b32_e32 v47, 16, v11
	v_lshlrev_b32_e32 v46, 16, v10
	v_and_b32_e32 v49, 0xffff0000, v11
	v_and_b32_e32 v48, 0xffff0000, v10
	v_pk_mul_f32 v[36:37], v[40:41], v[36:37] op_sel_hi:[0,1]
	v_pk_mul_f32 v[38:39], v[40:41], v[38:39] op_sel_hi:[0,1]
	v_pk_mul_f32 v[46:47], v[40:41], v[46:47] op_sel_hi:[0,1]
	v_pk_mul_f32 v[40:41], v[40:41], v[48:49] op_sel_hi:[0,1]
	v_bfe_u32 v43, v41, 16, 1
	v_bfe_u32 v45, v40, 16, 1
	v_bfe_u32 v48, v39, 16, 1
	v_bfe_u32 v49, v38, 16, 1
	v_add3_u32 v49, v38, v49, s65
	v_add3_u32 v48, v39, v48, s65
	v_add3_u32 v38, v40, v45, s65
	v_add3_u32 v39, v41, v43, s65
	v_bfe_u32 v40, v36, 16, 1
	v_bfe_u32 v41, v37, 16, 1
	v_bfe_u32 v43, v46, 16, 1
	v_bfe_u32 v45, v47, 16, 1
	v_add3_u32 v45, v47, v45, s65
	v_add3_u32 v43, v46, v43, s65
	v_add3_u32 v37, v37, v41, s65
	v_add3_u32 v36, v36, v40, s65
	v_lshrrev_b32_e32 v36, 16, v36
	v_lshrrev_b32_e32 v37, 16, v37
	v_lshrrev_b32_e32 v40, 16, v43
	v_lshrrev_b32_e32 v41, 16, v45
	v_and_or_b32 v39, v39, s61, v41
	v_and_or_b32 v38, v38, s61, v40
	v_and_or_b32 v37, v48, s61, v37
	v_and_or_b32 v36, v49, s61, v36
	ds_write_b128 v135, v[36:39] offset:8192
	ds_write_b128 v135, v[12:15] offset:40960
	v_lshlrev_b32_e32 v37, 16, v17
	v_lshlrev_b32_e32 v36, 16, v16
	v_and_b32_e32 v39, 0xffff0000, v17
	v_and_b32_e32 v38, 0xffff0000, v16
	v_lshlrev_b32_e32 v41, 16, v19
	v_lshlrev_b32_e32 v40, 16, v18
	v_and_b32_e32 v47, 0xffff0000, v19
	v_and_b32_e32 v46, 0xffff0000, v18
	v_pk_mul_f32 v[36:37], v[42:43], v[36:37] op_sel_hi:[0,1]
	v_pk_mul_f32 v[38:39], v[42:43], v[38:39] op_sel_hi:[0,1]
	v_pk_mul_f32 v[40:41], v[42:43], v[40:41] op_sel_hi:[0,1]
	v_pk_mul_f32 v[42:43], v[42:43], v[46:47] op_sel_hi:[0,1]
	v_bfe_u32 v45, v43, 16, 1
	v_bfe_u32 v46, v42, 16, 1
	v_bfe_u32 v47, v39, 16, 1
	v_bfe_u32 v48, v38, 16, 1
	v_add3_u32 v48, v38, v48, s65
	v_add3_u32 v47, v39, v47, s65
	v_add3_u32 v38, v42, v46, s65
	v_add3_u32 v39, v43, v45, s65
	v_bfe_u32 v42, v36, 16, 1
	v_bfe_u32 v43, v37, 16, 1
	v_bfe_u32 v45, v40, 16, 1
	v_bfe_u32 v46, v41, 16, 1
	v_add3_u32 v41, v41, v46, s65
	v_add3_u32 v40, v40, v45, s65
	v_add3_u32 v37, v37, v43, s65
	v_add3_u32 v36, v36, v42, s65
	v_lshrrev_b32_e32 v36, 16, v36
	v_lshrrev_b32_e32 v37, 16, v37
	v_lshrrev_b32_e32 v40, 16, v40
	v_lshrrev_b32_e32 v41, 16, v41
	v_and_or_b32 v39, v39, s61, v41
	v_and_or_b32 v38, v38, s61, v40
	v_and_or_b32 v37, v47, s61, v37
	v_and_or_b32 v36, v48, s61, v36
	ds_write_b128 v135, v[36:39] offset:16384
	ds_write_b128 v135, v[20:23] offset:49152
	v_and_b32_e32 v39, 0xffff0000, v25
	v_and_b32_e32 v38, 0xffff0000, v24
	v_and_b32_e32 v43, 0xffff0000, v27
	v_and_b32_e32 v42, 0xffff0000, v26
	v_lshlrev_b32_e32 v37, 16, v25
	v_lshlrev_b32_e32 v36, 16, v24
	v_pk_mul_f32 v[38:39], v[44:45], v[38:39] op_sel_hi:[0,1]
	v_lshlrev_b32_e32 v41, 16, v27
	v_lshlrev_b32_e32 v40, 16, v26
	v_pk_mul_f32 v[42:43], v[44:45], v[42:43] op_sel_hi:[0,1]
	v_pk_mul_f32 v[36:37], v[44:45], v[36:37] op_sel_hi:[0,1]
	v_pk_mul_f32 v[40:41], v[44:45], v[40:41] op_sel_hi:[0,1]
	v_bfe_u32 v44, v43, 16, 1
	v_bfe_u32 v45, v42, 16, 1
	v_bfe_u32 v46, v39, 16, 1
	v_bfe_u32 v47, v38, 16, 1
	v_add3_u32 v47, v38, v47, s65
	v_add3_u32 v46, v39, v46, s65
	v_add3_u32 v38, v42, v45, s65
	v_add3_u32 v39, v43, v44, s65
	v_bfe_u32 v42, v36, 16, 1
	v_bfe_u32 v43, v37, 16, 1
	v_bfe_u32 v44, v40, 16, 1
	v_bfe_u32 v45, v41, 16, 1
	s_add_i32 s24, s24, s96
	v_add3_u32 v41, v41, v45, s65
	v_add3_u32 v40, v40, v44, s65
	v_add3_u32 v37, v37, v43, s65
	v_add3_u32 v36, v36, v42, s65
	s_cmpk_gt_i32 s24, 0x3ff
	v_lshrrev_b32_e32 v36, 16, v36
	v_lshrrev_b32_e32 v37, 16, v37
	v_lshrrev_b32_e32 v40, 16, v40
	v_lshrrev_b32_e32 v41, 16, v41
	s_cselect_b64 s[0:1], -1, 0
	v_and_or_b32 v39, v39, s61, v41
	v_and_or_b32 v38, v38, s61, v40
	v_and_or_b32 v37, v46, s61, v37
	v_and_or_b32 v36, v47, s61, v36
	s_and_b64 vcc, exec, s[0:1]
	ds_write_b128 v135, v[36:39] offset:24576
	ds_write_b128 v135, v[28:31] offset:57344
	s_waitcnt lgkmcnt(0)
	s_barrier
	s_cbranch_vccnz .LBB0_488
	s_ashr_i32 s3, s24, 31
	s_lshr_b32 s3, s3, 22
	s_add_i32 s3, s24, s3
	s_and_b32 s3, s3, 0xfffffc00
	s_sub_i32 s3, s24, s3
	s_lshl_b32 s4, s3, 4
	s_and_b32 s41, s4, 0xffffff80
	v_add_u32_e32 v26, s41, v92
	v_mov_b64_e32 v[24:25], s[28:29]
	s_bfe_u32 s25, s3, 0x20001
	v_mad_i64_i32 v[0:1], s[4:5], v26, s91, v[24:25]
	s_lshl_b32 s4, s25, 8
	s_mov_b32 s5, s48
	v_lshl_add_u64 v[0:1], v[0:1], 0, s[4:5]
	v_add_u32_e32 v8, 32, v26
	v_lshl_add_u64 v[0:1], v[0:1], 0, v[178:179]
	s_mov_b32 s42, 0x1b801000
	v_mad_i64_i32 v[8:9], s[26:27], v8, s91, v[24:25]
	v_add_co_u32_e32 v4, vcc, s42, v0
	v_lshl_add_u64 v[8:9], v[8:9], 0, s[4:5]
	v_add_u32_e32 v16, 64, v26
	v_addc_co_u32_e32 v5, vcc, 0, v1, vcc
	v_lshl_add_u64 v[8:9], v[8:9], 0, v[178:179]
	v_mad_i64_i32 v[16:17], s[26:27], v16, s91, v[24:25]
	v_add_co_u32_e32 v12, vcc, s42, v8
	v_lshl_add_u64 v[16:17], v[16:17], 0, s[4:5]
	v_add_u32_e32 v26, 0x60, v26
	v_or_b32_e32 v36, s41, v93
	v_addc_co_u32_e32 v13, vcc, 0, v9, vcc
	v_lshl_add_u64 v[16:17], v[16:17], 0, v[178:179]
	v_mad_i64_i32 v[24:25], s[26:27], v26, s91, v[24:25]
	v_ashrrev_i32_e32 v37, 31, v36
	v_add_co_u32_e32 v20, vcc, s42, v16
	v_lshl_add_u64 v[24:25], v[24:25], 0, s[4:5]
	v_lshlrev_b64 v[36:37], 6, v[36:37]
	s_lshl_b32 s3, s3, 5
	v_addc_co_u32_e32 v21, vcc, 0, v17, vcc
	v_lshl_add_u64 v[24:25], v[24:25], 0, v[178:179]
	v_lshl_add_u64 v[36:37], s[34:35], 0, v[36:37]
	s_and_b32 s4, s3, 32
	v_add_co_u32_e32 v28, vcc, s42, v24
	v_lshl_add_u64 v[36:37], v[36:37], 0, s[4:5]
	s_lshl_b32 s4, s25, 2
	v_addc_co_u32_e32 v29, vcc, 0, v25, vcc
	v_lshl_add_u64 v[36:37], v[36:37], 0, s[4:5]
	global_load_dwordx4 v[0:3], v[4:5], off
	s_nop 0
	global_load_dwordx4 v[4:7], v[4:5], off offset:1024
	s_nop 0
	global_load_dwordx4 v[8:11], v[12:13], off
	s_nop 0
	global_load_dwordx4 v[12:15], v[12:13], off offset:1024
	s_nop 0
	global_load_dwordx4 v[16:19], v[20:21], off
	s_nop 0
	global_load_dwordx4 v[20:23], v[20:21], off offset:1024
	s_nop 0
	global_load_dwordx4 v[24:27], v[28:29], off
	s_nop 0
	global_load_dwordx4 v[28:31], v[28:29], off offset:1024
	s_nop 0
	global_load_dword v107, v[36:37], off
	global_load_dword v108, v[36:37], off offset:16
	global_load_dword v109, v[36:37], off offset:64
	global_load_dword v110, v[36:37], off offset:80

.LBB0_584:
	s_waitcnt vmcnt(17)
	v_cvt_pk_bf16_f32 v78, v28, v29
	v_bfe_u32 v49, v30, 16, 1
	v_add3_u32 v49, v30, v49, s65
	v_bfe_u32 v53, v31, 16, 1
	v_lshrrev_b32_e32 v49, 16, v49
	v_add3_u32 v53, v31, v53, s65
	v_lshlrev_b64 v[80:81], 15, v[72:73]
	v_and_or_b32 v79, v53, s61, v49
	v_lshl_add_u64 v[80:81], v[40:41], 0, v[80:81]
	global_store_dwordx2 v[80:81], v[78:79], off
	s_or_b64 exec, exec, s[26:27]
	s_and_saveexec_b64 s[26:27], s[4:5]
	s_cbranch_execnz .LBB0_555
	s_branch .LBB0_556

.LBB0_586:
	v_cvt_pk_bf16_f32 v32, v28, v29
	v_cvt_pk_bf16_f32 v33, v30, v31
	v_lshlrev_b64 v[34:35], 15, v[68:69]
	v_lshl_add_u64 v[34:35], v[40:41], 0, v[34:35]
	global_store_dwordx2 v[34:35], v[32:33], off
	s_or_b64 exec, exec, s[26:27]
	s_and_saveexec_b64 s[26:27], s[4:5]
	s_cbranch_execnz .LBB0_559
	s_branch .LBB0_560

.LBB0_588:
	v_cvt_pk_bf16_f32 v28, v24, v25
	v_cvt_pk_bf16_f32 v29, v26, v27
	v_lshlrev_b64 v[30:31], 15, v[64:65]
	v_lshl_add_u64 v[30:31], v[40:41], 0, v[30:31]
	global_store_dwordx2 v[30:31], v[28:29], off
	s_or_b64 exec, exec, s[26:27]
	s_and_saveexec_b64 s[26:27], s[4:5]
	s_cbranch_execnz .LBB0_563
	s_branch .LBB0_564

.LBB0_590:
	v_cvt_pk_bf16_f32 v24, v20, v21
	v_cvt_pk_bf16_f32 v25, v22, v23
	v_lshlrev_b64 v[26:27], 15, v[60:61]
	v_lshl_add_u64 v[26:27], v[40:41], 0, v[26:27]
	global_store_dwordx2 v[26:27], v[24:25], off
	s_or_b64 exec, exec, s[26:27]
	s_and_saveexec_b64 s[26:27], s[4:5]
	s_cbranch_execnz .LBB0_567
	s_branch .LBB0_568

.LBB0_592:
	v_cvt_pk_bf16_f32 v20, v16, v17
	v_cvt_pk_bf16_f32 v21, v18, v19
	v_lshlrev_b64 v[22:23], 15, v[56:57]
	v_lshl_add_u64 v[22:23], v[40:41], 0, v[22:23]
	global_store_dwordx2 v[22:23], v[20:21], off
	s_or_b64 exec, exec, s[26:27]
	s_and_saveexec_b64 s[26:27], s[4:5]
	s_cbranch_execnz .LBB0_571
	s_branch .LBB0_572

.LBB0_594:
	v_cvt_pk_bf16_f32 v16, v12, v13
	v_cvt_pk_bf16_f32 v17, v14, v15
	v_lshlrev_b64 v[18:19], 15, v[52:53]
	v_lshl_add_u64 v[18:19], v[40:41], 0, v[18:19]
	global_store_dwordx2 v[18:19], v[16:17], off
	s_or_b64 exec, exec, s[26:27]
	s_and_saveexec_b64 s[26:27], s[4:5]
	s_cbranch_execnz .LBB0_575
	s_branch .LBB0_576

.LBB0_596:
	v_cvt_pk_bf16_f32 v12, v8, v9
	v_cvt_pk_bf16_f32 v13, v10, v11
	v_lshlrev_b64 v[14:15], 15, v[48:49]
	v_lshl_add_u64 v[14:15], v[40:41], 0, v[14:15]
	global_store_dwordx2 v[14:15], v[12:13], off
	s_or_b64 exec, exec, s[26:27]
	s_and_saveexec_b64 s[26:27], s[4:5]
	s_cbranch_execnz .LBB0_579
	s_branch .LBB0_580

.LBB0_598:
	v_cvt_pk_bf16_f32 v8, v4, v5
	v_cvt_pk_bf16_f32 v9, v6, v7
	v_lshlrev_b64 v[10:11], 15, v[44:45]
	v_lshl_add_u64 v[10:11], v[40:41], 0, v[10:11]
	global_store_dwordx2 v[10:11], v[8:9], off
	s_or_b64 exec, exec, s[26:27]
	s_and_saveexec_b64 s[26:27], s[4:5]
	s_cbranch_execz .LBB0_551

.LBB0_611:
	s_or_saveexec_b64 s[22:23], s[22:23]
	v_mov_b64_e32 v[52:53], 0x18000000
	v_mov_b64_e32 v[54:55], 9
	v_ashrrev_i32_e32 v51, 31, v50
	s_xor_b64 exec, exec, s[22:23]
	s_cbranch_execz .LBB0_613
	v_lshlrev_b64 v[52:53], 15, v[50:51]
	v_lshl_add_u64 v[52:53], s[14:15], 0, v[52:53]
	v_lshlrev_b64 v[54:55], 1, v[46:47]
	v_lshl_add_u64 v[52:53], v[52:53], 0, v[54:55]
	global_store_dwordx2 v[52:53], v[36:37], off
	s_waitcnt vmcnt(3)
	v_cvt_pk_bf16_f32 v52, v28, v29
	v_bfe_u32 v53, v30, 16, 1
	v_add3_u32 v53, v30, v53, s65
	v_bfe_u32 v75, v31, 16, 1
	v_lshlrev_b64 v[76:77], 15, v[44:45]
	v_lshrrev_b32_e32 v53, 16, v53
	v_add3_u32 v75, v31, v75, s65
	v_lshl_add_u64 v[76:77], s[14:15], 0, v[76:77]
	v_and_or_b32 v53, v75, s61, v53
	v_lshl_add_u64 v[54:55], v[76:77], 0, v[54:55]
	global_store_dwordx2 v[54:55], v[52:53], off
	v_mov_b64_e32 v[52:53], 0x14000000
	v_mov_b64_e32 v[54:55], 16

.LBB0_618:
	s_or_saveexec_b64 s[4:5], s[4:5]
	v_mov_b64_e32 v[34:35], 0x18000000
	v_mov_b64_e32 v[44:45], 9
	v_ashrrev_i32_e32 v29, 31, v28
	v_ashrrev_i32_e32 v31, 31, v30
	s_xor_b64 exec, exec, s[4:5]
	s_cbranch_execz .LBB0_620
	v_lshlrev_b64 v[34:35], 15, v[28:29]
	v_ashrrev_i32_e32 v33, 31, v32
	v_lshl_add_u64 v[34:35], s[14:15], 0, v[34:35]
	v_lshlrev_b64 v[44:45], 1, v[32:33]
	v_lshl_add_u64 v[34:35], v[34:35], 0, v[44:45]
	global_store_dwordx2 v[34:35], v[36:37], off
	v_cvt_pk_bf16_f32 v34, v4, v5
	v_cvt_pk_bf16_f32 v35, v6, v7
	v_lshlrev_b64 v[50:51], 15, v[30:31]
	v_lshl_add_u64 v[50:51], s[14:15], 0, v[50:51]
	v_lshl_add_u64 v[44:45], v[50:51], 0, v[44:45]
	global_store_dwordx2 v[44:45], v[34:35], off
	v_mov_b64_e32 v[34:35], 0x14000000
	v_mov_b64_e32 v[44:45], 16

.LBB0_625:
	s_or_saveexec_b64 s[2:3], s[2:3]
	v_mov_b64_e32 v[34:35], 0x18000000
	v_mov_b64_e32 v[44:45], 9
	v_ashrrev_i32_e32 v29, 31, v28
	v_ashrrev_i32_e32 v31, 31, v30
	s_xor_b64 exec, exec, s[2:3]
	s_cbranch_execz .LBB0_627
	v_lshlrev_b64 v[34:35], 15, v[28:29]
	v_ashrrev_i32_e32 v33, 31, v32
	v_lshl_add_u64 v[34:35], s[14:15], 0, v[34:35]
	v_lshlrev_b64 v[44:45], 1, v[32:33]
	v_lshl_add_u64 v[34:35], v[34:35], 0, v[44:45]
	global_store_dwordx2 v[34:35], v[36:37], off
	v_cvt_pk_bf16_f32 v34, v20, v21
	v_cvt_pk_bf16_f32 v35, v22, v23
	v_lshlrev_b64 v[50:51], 15, v[30:31]
	v_lshl_add_u64 v[50:51], s[14:15], 0, v[50:51]
	v_lshl_add_u64 v[44:45], v[50:51], 0, v[44:45]
	global_store_dwordx2 v[44:45], v[34:35], off
	v_mov_b64_e32 v[34:35], 0x14000000
	v_mov_b64_e32 v[44:45], 16

.LBB0_632:
	s_or_saveexec_b64 s[0:1], s[0:1]
	v_mov_b64_e32 v[34:35], 0x18000000
	v_mov_b64_e32 v[44:45], 9
	v_ashrrev_i32_e32 v29, 31, v28
	v_ashrrev_i32_e32 v31, 31, v30
	s_xor_b64 exec, exec, s[0:1]
	s_cbranch_execz .LBB0_634
	v_lshlrev_b64 v[34:35], 15, v[28:29]
	v_ashrrev_i32_e32 v33, 31, v32
	v_lshl_add_u64 v[34:35], s[14:15], 0, v[34:35]
	v_lshlrev_b64 v[44:45], 1, v[32:33]
	v_lshl_add_u64 v[34:35], v[34:35], 0, v[44:45]
	global_store_dwordx2 v[34:35], v[36:37], off
	v_cvt_pk_bf16_f32 v34, v24, v25
	v_cvt_pk_bf16_f32 v35, v26, v27
	v_lshlrev_b64 v[50:51], 15, v[30:31]
	v_lshl_add_u64 v[50:51], s[14:15], 0, v[50:51]
	v_lshl_add_u64 v[44:45], v[50:51], 0, v[44:45]
	global_store_dwordx2 v[44:45], v[34:35], off
	v_mov_b64_e32 v[34:35], 0x14000000
	v_mov_b64_e32 v[44:45], 16

.LBB0_921:
	s_waitcnt vmcnt(7)
	v_and_b32_e32 v181, 0xffff0000, v208
	v_and_b32_e32 v183, 0xffff0000, v209
	v_lshlrev_b32_e32 v180, 16, v208
	v_lshlrev_b32_e32 v182, 16, v209
	v_mul_f32_e32 v208, v183, v183
	s_waitcnt vmcnt(6)
	v_lshlrev_b32_e32 v211, 16, v207
	v_lshlrev_b32_e32 v210, 16, v206
	v_and_b32_e32 v207, 0xffff0000, v207
	v_and_b32_e32 v206, 0xffff0000, v206
	s_waitcnt vmcnt(4)
	v_lshlrev_b32_e32 v233, 16, v202
	v_mul_f32_e32 v232, v181, v181
	v_pk_fma_f32 v[208:209], v[182:183], v[182:183], v[208:209] op_sel_hi:[1,1,0]
	v_pk_mul_f32 v[212:213], v[206:207], v[206:207]
	v_pk_fma_f32 v[236:237], v[180:181], v[180:181], v[232:233] op_sel_hi:[1,1,0]
	v_pk_fma_f32 v[212:213], v[210:211], v[210:211], v[212:213]
	v_and_b32_e32 v235, 0xffff0000, v202
	v_mov_b32_e32 v232, v236
	v_mov_b32_e32 v238, v208
	v_mov_b32_e32 v239, v233
	v_mul_f32_e32 v234, v235, v235
	v_pk_add_f32 v[208:209], v[236:237], v[208:209]
	v_pk_mul_f32 v[236:237], v[232:233], v[238:239]
	v_pk_add_f32 v[212:213], v[212:213], v[212:213] op_sel:[0,1] op_sel_hi:[1,0]
	v_lshlrev_b32_e32 v230, 16, v204
	v_and_b32_e32 v231, 0xffff0000, v204
	v_lshlrev_b32_e32 v204, 16, v205
	v_and_b32_e32 v205, 0xffff0000, v205
	v_mov_b32_e32 v209, v237
	v_mov_b32_e32 v213, v234
	v_lshlrev_b32_e32 v202, 16, v203
	v_and_b32_e32 v203, 0xffff0000, v203
	v_pk_add_f32 v[208:209], v[208:209], v[212:213]
	v_mul_f32_e32 v212, v231, v231
	v_mul_f32_e32 v232, v205, v205
	v_mul_f32_e32 v240, v202, v202
	v_mul_f32_e32 v241, v203, v203
	v_pk_fma_f32 v[212:213], v[230:231], v[230:231], v[212:213] op_sel_hi:[1,1,0]
	v_pk_fma_f32 v[236:237], v[204:205], v[204:205], v[232:233] op_sel_hi:[1,1,0]
	v_mov_b32_e32 v213, v240
	v_mov_b32_e32 v237, v241
	v_pk_add_f32 v[212:213], v[212:213], v[236:237]
	s_waitcnt vmcnt(2)
	v_lshlrev_b32_e32 v239, 16, v199
	v_pk_add_f32 v[208:209], v[208:209], v[212:213]
	v_lshlrev_b32_e32 v213, 16, v201
	v_lshlrev_b32_e32 v212, 16, v200
	v_and_b32_e32 v201, 0xffff0000, v201
	v_and_b32_e32 v200, 0xffff0000, v200
	v_pk_mul_f32 v[236:237], v[200:201], v[200:201]
	v_lshlrev_b32_e32 v238, 16, v198
	v_pk_fma_f32 v[236:237], v[212:213], v[212:213], v[236:237]
	v_and_b32_e32 v199, 0xffff0000, v199
	v_pk_add_f32 v[236:237], v[236:237], v[236:237] op_sel:[0,1] op_sel_hi:[1,0]
	v_and_b32_e32 v198, 0xffff0000, v198
	s_waitcnt vmcnt(0)
	v_lshlrev_b32_e32 v245, 16, v194
	v_pk_add_f32 v[208:209], v[208:209], v[208:209] op_sel:[0,1] op_sel_hi:[1,0]
	v_pk_mul_f32 v[240:241], v[198:199], v[198:199]
	v_mov_b32_e32 v244, v208
	v_mov_b32_e32 v248, v236
	v_mov_b32_e32 v249, v245
	v_pk_fma_f32 v[240:241], v[238:239], v[238:239], v[240:241]
	v_and_b32_e32 v247, 0xffff0000, v194
	v_pk_add_f32 v[208:209], v[208:209], v[236:237]
	v_pk_mul_f32 v[236:237], v[244:245], v[248:249]
	v_and_b32_e32 v243, 0xffff0000, v196
	v_mul_f32_e32 v232, v247, v247
	v_mov_b32_e32 v209, v237
	v_pk_add_f32 v[236:237], v[240:241], v[240:241] op_sel:[0,1] op_sel_hi:[1,0]
	v_lshlrev_b32_e32 v242, 16, v196
	v_lshlrev_b32_e32 v196, 16, v197
	v_and_b32_e32 v197, 0xffff0000, v197
	v_mov_b32_e32 v237, v232
	v_mul_f32_e32 v232, v243, v243
	v_lshlrev_b32_e32 v194, 16, v195
	v_and_b32_e32 v195, 0xffff0000, v195
	v_pk_add_f32 v[208:209], v[208:209], v[236:237]
	v_pk_fma_f32 v[236:237], v[242:243], v[242:243], v[232:233] op_sel_hi:[1,1,0]
	v_mul_f32_e32 v232, v197, v197
	v_mul_f32_e32 v234, v194, v194
	v_mul_f32_e32 v246, v195, v195
	v_pk_fma_f32 v[240:241], v[196:197], v[196:197], v[232:233] op_sel_hi:[1,1,0]
	v_mov_b32_e32 v237, v234
	v_mov_b32_e32 v241, v246
	v_pk_add_f32 v[236:237], v[236:237], v[240:241]
	v_mov_b32_e32 v234, v233
	v_pk_add_f32 v[208:209], v[208:209], v[236:237]
	v_mov_b32_e32 v246, v245
	v_add_f32_e32 v208, v208, v209
	ds_bpermute_b32 v209, v129, v208
	s_add_u32 s24, s24, 1
	s_addc_u32 s25, s25, 0
	s_add_u32 s26, s26, 0x1000
	s_addc_u32 s27, s27, 0
	s_waitcnt lgkmcnt(0)
	v_add_f32_e32 v208, v208, v209
	ds_bpermute_b32 v209, v225, v208
	s_add_i32 s35, s35, 1
	s_cmp_ge_i32 s35, s34
	s_waitcnt lgkmcnt(0)
	v_add_f32_e32 v208, v208, v209
	ds_bpermute_b32 v209, v226, v208
	s_waitcnt lgkmcnt(0)
	v_add_f32_e32 v208, v208, v209
	ds_bpermute_b32 v209, v227, v208
	s_waitcnt lgkmcnt(0)
	v_add_f32_e32 v208, v208, v209
	ds_bpermute_b32 v209, v228, v208
	s_waitcnt lgkmcnt(0)
	v_add_f32_e32 v208, v208, v209
	ds_bpermute_b32 v209, v229, v208
	s_waitcnt lgkmcnt(0)
	v_add_f32_e32 v208, v208, v209
	v_fmamk_f32 v208, v208, 0x3a000000, v252
	v_mul_f32_e32 v209, 0x4b800000, v208
	v_cmp_gt_f32_e32 vcc, s88, v208
	s_nop 1
	v_cndmask_b32_e32 v208, v208, v209, vcc
	v_rsq_f32_e32 v208, v208
	s_nop 0
	v_mul_f32_e32 v209, 0x45800000, v208
	v_cndmask_b32_e32 v208, v208, v209, vcc
	v_pk_mul_f32 v[180:181], v[208:209], v[180:181] op_sel_hi:[0,1]
	v_pk_mul_f32 v[180:181], v[32:33], v[180:181]
	v_pk_mul_f32 v[182:183], v[208:209], v[182:183] op_sel_hi:[0,1]
	v_pk_fma_f32 v[0:1], v[64:65], v[180:181], v[0:1]
	v_mov_b32_e32 v180, v211
	v_mov_b32_e32 v181, v207
	v_pk_mul_f32 v[180:181], v[208:209], v[180:181] op_sel_hi:[0,1]
	v_pk_mul_f32 v[180:181], v[38:39], v[180:181]
	v_pk_mul_f32 v[182:183], v[34:35], v[182:183]
	v_pk_fma_f32 v[6:7], v[70:71], v[180:181], v[6:7]
	v_pk_mul_f32 v[180:181], v[208:209], v[204:205] op_sel_hi:[0,1]
	v_pk_mul_f32 v[180:181], v[42:43], v[180:181]
	v_mov_b32_e32 v211, v206
	v_pk_fma_f32 v[10:11], v[74:75], v[180:181], v[10:11]
	v_pk_mul_f32 v[180:181], v[202:203], v[208:209] op_sel_hi:[1,0]
	v_pk_fma_f32 v[2:3], v[66:67], v[182:183], v[2:3]
	v_pk_mul_f32 v[180:181], v[46:47], v[180:181]
	v_pk_mul_f32 v[182:183], v[208:209], v[210:211] op_sel_hi:[0,1]
	v_pk_fma_f32 v[14:15], v[78:79], v[180:181], v[14:15]
	v_mov_b32_e32 v180, v213
	v_mov_b32_e32 v181, v201
	v_pk_mul_f32 v[182:183], v[36:37], v[182:183]
	v_pk_mul_f32 v[180:181], v[208:209], v[180:181] op_sel_hi:[0,1]
	v_pk_fma_f32 v[4:5], v[68:69], v[182:183], v[4:5]
	v_pk_mul_f32 v[182:183], v[208:209], v[230:231] op_sel_hi:[0,1]
	v_pk_mul_f32 v[180:181], v[50:51], v[180:181]
	v_pk_mul_f32 v[182:183], v[40:41], v[182:183]
	v_pk_fma_f32 v[18:19], v[82:83], v[180:181], v[18:19]
	v_mov_b32_e32 v180, v239
	v_mov_b32_e32 v181, v199
	v_pk_fma_f32 v[8:9], v[72:73], v[182:183], v[8:9]
	v_pk_mul_f32 v[182:183], v[234:235], v[208:209] op_sel_hi:[1,0]
	v_pk_mul_f32 v[180:181], v[208:209], v[180:181] op_sel_hi:[0,1]
	v_pk_mul_f32 v[182:183], v[44:45], v[182:183]
	v_mov_b32_e32 v213, v200
	v_pk_mul_f32 v[180:181], v[54:55], v[180:181]
	v_pk_fma_f32 v[12:13], v[76:77], v[182:183], v[12:13]
	v_pk_mul_f32 v[182:183], v[208:209], v[212:213] op_sel_hi:[0,1]
	v_pk_fma_f32 v[22:23], v[86:87], v[180:181], v[22:23]
	v_pk_mul_f32 v[180:181], v[208:209], v[196:197] op_sel_hi:[0,1]
	v_pk_mul_f32 v[182:183], v[48:49], v[182:183]
	v_mov_b32_e32 v239, v198
	v_pk_mul_f32 v[180:181], v[58:59], v[180:181]
	v_pk_fma_f32 v[16:17], v[80:81], v[182:183], v[16:17]
	v_pk_mul_f32 v[182:183], v[208:209], v[238:239] op_sel_hi:[0,1]
	v_pk_fma_f32 v[26:27], v[90:91], v[180:181], v[26:27]
	v_pk_mul_f32 v[180:181], v[194:195], v[208:209] op_sel_hi:[1,0]
	v_pk_mul_f32 v[182:183], v[52:53], v[182:183]
	v_pk_mul_f32 v[180:181], v[62:63], v[180:181]
	v_pk_fma_f32 v[20:21], v[84:85], v[182:183], v[20:21]
	v_pk_mul_f32 v[182:183], v[208:209], v[242:243] op_sel_hi:[0,1]
	v_pk_fma_f32 v[30:31], v[94:95], v[180:181], v[30:31]
	v_pk_mul_f32 v[182:183], v[56:57], v[182:183]
	v_pk_fma_f32 v[24:25], v[88:89], v[182:183], v[24:25]
	v_pk_mul_f32 v[182:183], v[246:247], v[208:209] op_sel_hi:[1,0]
	v_pk_mul_f32 v[182:183], v[60:61], v[182:183]
	v_cvt_pk_bf16_f32 v180, v0, v1
	v_pk_fma_f32 v[28:29], v[92:93], v[182:183], v[28:29]
	v_lshl_add_u64 v[194:195], v[164:165], 0, s[28:29]
	v_cvt_pk_bf16_f32 v181, v2, v3
	global_store_dwordx2 v[194:195], v[180:181], off
	v_cvt_pk_bf16_f32 v180, v4, v5
	v_cvt_pk_bf16_f32 v181, v6, v7
	global_store_dwordx2 v[194:195], v[180:181], off offset:512
	v_cvt_pk_bf16_f32 v180, v8, v9
	v_cvt_pk_bf16_f32 v181, v10, v11
	global_store_dwordx2 v[194:195], v[180:181], off offset:1024
	v_cvt_pk_bf16_f32 v180, v12, v13
	v_cvt_pk_bf16_f32 v181, v14, v15
	global_store_dwordx2 v[194:195], v[180:181], off offset:1536
	v_cvt_pk_bf16_f32 v180, v16, v17
	v_cvt_pk_bf16_f32 v181, v18, v19
	global_store_dwordx2 v[194:195], v[180:181], off offset:2048
	v_cvt_pk_bf16_f32 v180, v20, v21
	v_mov_b32_e32 v196, v1
	v_mov_b32_e32 v197, v5
	v_cvt_pk_bf16_f32 v181, v22, v23
	v_mov_b32_e32 v182, v0
	v_mov_b32_e32 v183, v4
	v_pk_mul_f32 v[196:197], v[196:197], v[196:197]
	v_mov_b32_e32 v198, v3
	v_mov_b32_e32 v199, v7
	v_pk_fma_f32 v[182:183], v[182:183], v[182:183], v[196:197]
	v_mov_b32_e32 v196, v2
	v_mov_b32_e32 v197, v6
	v_pk_mul_f32 v[198:199], v[198:199], v[198:199]
	global_store_dwordx2 v[194:195], v[180:181], off offset:2560
	v_pk_fma_f32 v[196:197], v[196:197], v[196:197], v[198:199]
	v_pk_mul_f32 v[198:199], v[8:9], v[8:9]
	v_pk_add_f32 v[182:183], v[182:183], v[196:197]
	v_pk_mul_f32 v[196:197], v[10:11], v[10:11]
	v_pk_add_f32 v[182:183], v[182:183], v[182:183] op_sel_hi:[0,1]
	v_pk_mov_b32 v[200:201], v[198:199], v[196:197] op_sel:[1,0]
	v_mov_b32_e32 v199, v197
	v_mul_f32_e32 v182, v12, v12
	v_pk_add_f32 v[196:197], v[200:201], v[198:199]
	v_pk_fma_f32 v[198:199], v[12:13], v[12:13], v[182:183] op_sel_hi:[1,1,0]
	v_mul_f32_e32 v182, v14, v14
	v_pk_add_f32 v[196:197], v[196:197], v[196:197] op_sel_hi:[0,1]
	v_pk_fma_f32 v[200:201], v[14:15], v[14:15], v[182:183] op_sel_hi:[1,1,0]
	v_mul_f32_e32 v198, v16, v16
	v_mul_f32_e32 v200, v17, v17
	v_mul_f32_e32 v196, v18, v18
	v_mul_f32_e32 v182, v19, v19
	v_pk_add_f32 v[198:199], v[198:199], v[200:201]
	v_pk_add_f32 v[182:183], v[196:197], v[182:183]
	v_pk_mul_f32 v[196:197], v[22:23], v[22:23]
	v_pk_add_f32 v[182:183], v[198:199], v[182:183]
	v_pk_mul_f32 v[198:199], v[20:21], v[20:21]
	v_pk_add_f32 v[182:183], v[182:183], v[182:183] op_sel_hi:[0,1]
	v_pk_mov_b32 v[200:201], v[198:199], v[196:197] op_sel:[1,0]
	v_mov_b32_e32 v199, v197
	v_mul_f32_e32 v182, v24, v24
	v_pk_add_f32 v[196:197], v[200:201], v[198:199]
	v_pk_fma_f32 v[198:199], v[24:25], v[24:25], v[182:183] op_sel_hi:[1,1,0]
	v_mul_f32_e32 v182, v26, v26
	v_pk_add_f32 v[196:197], v[196:197], v[196:197] op_sel_hi:[0,1]
	v_pk_fma_f32 v[200:201], v[26:27], v[26:27], v[182:183] op_sel_hi:[1,1,0]
	v_mul_f32_e32 v198, v28, v28
	v_mul_f32_e32 v200, v29, v29
	v_mul_f32_e32 v196, v30, v30
	v_mul_f32_e32 v182, v31, v31
	v_pk_add_f32 v[198:199], v[198:199], v[200:201]
	v_pk_add_f32 v[182:183], v[196:197], v[182:183]
	s_nop 0
	v_pk_add_f32 v[182:183], v[198:199], v[182:183]
	s_nop 0
	v_add_f32_e32 v182, v182, v183
	ds_bpermute_b32 v183, v129, v182
	s_nop 0
	s_nop 0
	s_nop 0
	v_mov_b64_e32 v[198:199], v[174:175]
	s_waitcnt lgkmcnt(0)
	v_add_f32_e32 v181, v182, v183
	ds_bpermute_b32 v182, v225, v181
	s_nop 0
	s_nop 0
	v_cvt_pk_bf16_f32 v180, v24, v25
	s_nop 0
	s_waitcnt lgkmcnt(0)
	v_add_f32_e32 v181, v181, v182
	ds_bpermute_b32 v182, v226, v181
	s_nop 0
	s_nop 0
	v_mov_b64_e32 v[200:201], v[184:185]
	v_mov_b64_e32 v[202:203], v[186:187]
	s_waitcnt lgkmcnt(0)
	v_add_f32_e32 v182, v181, v182
	ds_bpermute_b32 v197, v227, v182
	v_cvt_pk_bf16_f32 v181, v26, v27
	global_store_dwordx2 v[194:195], v[180:181], off offset:3072
	s_nop 0
	s_nop 0
	s_waitcnt lgkmcnt(0)
	v_add_f32_e32 v181, v182, v197
	ds_bpermute_b32 v182, v228, v181
	s_nop 0
	s_nop 0
	s_nop 0
	v_cvt_pk_bf16_f32 v180, v28, v29
	s_waitcnt lgkmcnt(0)
	v_add_f32_e32 v181, v181, v182
	ds_bpermute_b32 v182, v229, v181
	s_nop 0
	s_nop 0
	s_nop 0
	s_nop 0
	s_waitcnt lgkmcnt(0)
	v_add_f32_e32 v181, v181, v182
	v_fmamk_f32 v181, v181, 0x3a000000, v252
	v_mul_f32_e32 v182, 0x4b800000, v181
	v_cmp_gt_f32_e32 vcc, s88, v181
	v_mov_b64_e32 v[204:205], v[188:189]
	v_mov_b64_e32 v[206:207], v[190:191]
	v_cndmask_b32_e32 v181, v181, v182, vcc
	v_rsq_f32_e32 v182, v181
	s_nop 0
	v_cvt_pk_bf16_f32 v181, v30, v31
	global_store_dwordx2 v[194:195], v[180:181], off offset:3584
	v_mul_f32_e32 v180, 0x45800000, v182
	v_cndmask_b32_e32 v180, v182, v180, vcc
	v_pk_mul_f32 v[194:195], v[0:1], v[180:181] op_sel_hi:[1,0]
	v_pk_mul_f32 v[196:197], v[2:3], v[180:181] op_sel_hi:[1,0]
	v_pk_fma_f32 v[194:195], v[132:133], v[194:195], v[96:97]
	v_pk_fma_f32 v[196:197], v[130:131], v[196:197], v[98:99]
	s_nop 0
	s_nop 0
	v_cvt_pk_bf16_f32 v194, v194, v195
	v_bfe_u32 v181, v196, 16, 1
	v_add3_u32 v181, v196, v181, s65
	v_bfe_u32 v195, v197, 16, 1
	v_lshrrev_b32_e32 v181, 16, v181
	v_add3_u32 v195, v197, v195, s65
	v_lshl_add_u64 v[182:183], v[166:167], 0, s[28:29]
	v_and_or_b32 v195, v195, s61, v181
	global_store_dwordx2 v[182:183], v[194:195], off
	v_pk_mul_f32 v[194:195], v[4:5], v[180:181] op_sel_hi:[1,0]
	v_pk_mul_f32 v[196:197], v[6:7], v[180:181] op_sel_hi:[1,0]
	v_pk_fma_f32 v[194:195], v[136:137], v[194:195], v[100:101]
	v_pk_fma_f32 v[196:197], v[134:135], v[196:197], v[102:103]
	v_cvt_pk_bf16_f32 v194, v194, v195
	v_bfe_u32 v181, v196, 16, 1
	v_add3_u32 v181, v196, v181, s65
	v_bfe_u32 v195, v197, 16, 1
	v_lshrrev_b32_e32 v181, 16, v181
	v_add3_u32 v195, v197, v195, s65
	v_and_or_b32 v195, v195, s61, v181
	global_store_dwordx2 v[182:183], v[194:195], off offset:512
	v_pk_mul_f32 v[194:195], v[8:9], v[180:181] op_sel_hi:[1,0]
	v_pk_mul_f32 v[196:197], v[10:11], v[180:181] op_sel_hi:[1,0]
	v_pk_fma_f32 v[194:195], v[140:141], v[194:195], v[104:105]
	v_pk_fma_f32 v[196:197], v[138:139], v[196:197], v[106:107]
	v_cvt_pk_bf16_f32 v194, v194, v195
	v_bfe_u32 v181, v196, 16, 1
	v_add3_u32 v181, v196, v181, s65
	v_bfe_u32 v195, v197, 16, 1
	v_lshrrev_b32_e32 v181, 16, v181
	v_add3_u32 v195, v197, v195, s65
	v_and_or_b32 v195, v195, s61, v181
	global_store_dwordx2 v[182:183], v[194:195], off offset:1024
	v_pk_mul_f32 v[194:195], v[12:13], v[180:181] op_sel_hi:[1,0]
	v_pk_mul_f32 v[196:197], v[14:15], v[180:181] op_sel_hi:[1,0]
	v_pk_fma_f32 v[194:195], v[144:145], v[194:195], v[108:109]
	v_pk_fma_f32 v[196:197], v[142:143], v[196:197], v[110:111]
	v_cvt_pk_bf16_f32 v194, v194, v195
	v_bfe_u32 v181, v196, 16, 1
	v_add3_u32 v181, v196, v181, s65
	v_bfe_u32 v195, v197, 16, 1
	v_lshrrev_b32_e32 v181, 16, v181
	v_add3_u32 v195, v197, v195, s65
	v_and_or_b32 v195, v195, s61, v181
	global_store_dwordx2 v[182:183], v[194:195], off offset:1536
	v_pk_mul_f32 v[194:195], v[16:17], v[180:181] op_sel_hi:[1,0]
	v_pk_mul_f32 v[196:197], v[18:19], v[180:181] op_sel_hi:[1,0]
	v_pk_fma_f32 v[194:195], v[148:149], v[194:195], v[112:113]
	v_pk_fma_f32 v[196:197], v[146:147], v[196:197], v[114:115]
	v_cvt_pk_bf16_f32 v194, v194, v195
	v_bfe_u32 v181, v196, 16, 1
	v_add3_u32 v181, v196, v181, s65
	v_bfe_u32 v195, v197, 16, 1
	v_lshrrev_b32_e32 v181, 16, v181
	v_add3_u32 v195, v197, v195, s65
	v_and_or_b32 v195, v195, s61, v181
	global_store_dwordx2 v[182:183], v[194:195], off offset:2048
	v_pk_mul_f32 v[194:195], v[20:21], v[180:181] op_sel_hi:[1,0]
	v_pk_mul_f32 v[196:197], v[22:23], v[180:181] op_sel_hi:[1,0]
	v_pk_fma_f32 v[194:195], v[152:153], v[194:195], v[116:117]
	v_pk_fma_f32 v[196:197], v[150:151], v[196:197], v[118:119]
	v_cvt_pk_bf16_f32 v194, v194, v195
	v_bfe_u32 v181, v196, 16, 1
	v_add3_u32 v181, v196, v181, s65
	v_bfe_u32 v195, v197, 16, 1
	v_lshrrev_b32_e32 v181, 16, v181
	v_add3_u32 v195, v197, v195, s65
	v_and_or_b32 v195, v195, s61, v181
	global_store_dwordx2 v[182:183], v[194:195], off offset:2560
	v_pk_mul_f32 v[194:195], v[24:25], v[180:181] op_sel_hi:[1,0]
	v_pk_mul_f32 v[196:197], v[26:27], v[180:181] op_sel_hi:[1,0]
	v_pk_fma_f32 v[194:195], v[156:157], v[194:195], v[120:121]
	v_pk_fma_f32 v[196:197], v[154:155], v[196:197], v[122:123]
	v_cvt_pk_bf16_f32 v194, v194, v195
	v_bfe_u32 v181, v196, 16, 1
	v_add3_u32 v181, v196, v181, s65
	v_bfe_u32 v195, v197, 16, 1
	v_lshrrev_b32_e32 v181, 16, v181
	v_add3_u32 v195, v197, v195, s65
	v_and_or_b32 v195, v195, s61, v181
	global_store_dwordx2 v[182:183], v[194:195], off offset:3072
	v_pk_mul_f32 v[194:195], v[28:29], v[180:181] op_sel_hi:[1,0]
	v_pk_mul_f32 v[180:181], v[30:31], v[180:181] op_sel_hi:[1,0]
	v_pk_fma_f32 v[194:195], v[160:161], v[194:195], v[124:125]
	v_pk_fma_f32 v[180:181], v[158:159], v[180:181], v[126:127]
	v_cvt_pk_bf16_f32 v194, v194, v195
	v_bfe_u32 v195, v180, 16, 1
	v_add3_u32 v180, v180, v195, s65
	v_bfe_u32 v195, v181, 16, 1
	v_lshrrev_b32_e32 v180, 16, v180
	v_add3_u32 v181, v181, v195, s65
	v_and_or_b32 v195, v181, s61, v180
	global_store_dwordx2 v[182:183], v[194:195], off offset:3584
	v_mov_b64_e32 v[194:195], v[170:171]
	v_mov_b64_e32 v[196:197], v[172:173]
	v_mov_b64_e32 v[208:209], v[192:193]
	s_cbranch_scc1 .LBB0_928

.LBB0_932:
	s_waitcnt vmcnt(23)
	v_lshlrev_b32_e32 v170, 16, v162
	v_and_b32_e32 v171, 0xffff0000, v162
	v_lshlrev_b32_e32 v162, 16, v163
	v_and_b32_e32 v163, 0xffff0000, v163
	v_mul_f32_e32 v172, v163, v163
	s_waitcnt vmcnt(22)
	v_lshlrev_b32_e32 v175, 16, v161
	v_lshlrev_b32_e32 v174, 16, v160
	v_and_b32_e32 v161, 0xffff0000, v161
	v_and_b32_e32 v160, 0xffff0000, v160
	s_waitcnt vmcnt(20)
	v_lshlrev_b32_e32 v185, 16, v156
	v_mul_f32_e32 v184, v171, v171
	v_pk_fma_f32 v[172:173], v[162:163], v[162:163], v[172:173] op_sel_hi:[1,1,0]
	v_pk_mul_f32 v[180:181], v[160:161], v[160:161]
	v_pk_fma_f32 v[188:189], v[170:171], v[170:171], v[184:185] op_sel_hi:[1,1,0]
	v_pk_fma_f32 v[180:181], v[174:175], v[174:175], v[180:181]
	v_and_b32_e32 v187, 0xffff0000, v156
	v_mov_b32_e32 v184, v188
	v_mov_b32_e32 v190, v172
	v_mov_b32_e32 v191, v185
	v_mul_f32_e32 v169, v187, v187
	v_pk_add_f32 v[172:173], v[188:189], v[172:173]
	v_pk_mul_f32 v[188:189], v[184:185], v[190:191]
	v_pk_add_f32 v[180:181], v[180:181], v[180:181] op_sel:[0,1] op_sel_hi:[1,0]
	v_lshlrev_b32_e32 v182, 16, v158
	v_and_b32_e32 v183, 0xffff0000, v158
	v_lshlrev_b32_e32 v158, 16, v159
	v_and_b32_e32 v159, 0xffff0000, v159
	v_mov_b32_e32 v173, v189
	v_mov_b32_e32 v181, v169
	v_lshlrev_b32_e32 v156, 16, v157
	v_and_b32_e32 v157, 0xffff0000, v157
	v_pk_add_f32 v[172:173], v[172:173], v[180:181]
	v_mul_f32_e32 v180, v183, v183
	v_mul_f32_e32 v184, v159, v159
	v_mul_f32_e32 v186, v156, v156
	v_mul_f32_e32 v192, v157, v157
	v_pk_fma_f32 v[180:181], v[182:183], v[182:183], v[180:181] op_sel_hi:[1,1,0]
	v_pk_fma_f32 v[188:189], v[158:159], v[158:159], v[184:185] op_sel_hi:[1,1,0]
	v_mov_b32_e32 v181, v186
	v_mov_b32_e32 v189, v192
	v_pk_add_f32 v[180:181], v[180:181], v[188:189]
	s_waitcnt vmcnt(18)
	v_lshlrev_b32_e32 v191, 16, v153
	v_pk_add_f32 v[172:173], v[172:173], v[180:181]
	v_lshlrev_b32_e32 v181, 16, v155
	v_lshlrev_b32_e32 v180, 16, v154
	v_and_b32_e32 v155, 0xffff0000, v155
	v_and_b32_e32 v154, 0xffff0000, v154
	v_pk_mul_f32 v[188:189], v[154:155], v[154:155]
	v_lshlrev_b32_e32 v190, 16, v152
	v_pk_fma_f32 v[188:189], v[180:181], v[180:181], v[188:189]
	v_and_b32_e32 v153, 0xffff0000, v153
	v_pk_add_f32 v[188:189], v[188:189], v[188:189] op_sel:[0,1] op_sel_hi:[1,0]
	v_and_b32_e32 v152, 0xffff0000, v152
	s_waitcnt vmcnt(16)
	v_lshlrev_b32_e32 v197, 16, v148
	v_pk_add_f32 v[172:173], v[172:173], v[172:173] op_sel:[0,1] op_sel_hi:[1,0]
	v_pk_mul_f32 v[192:193], v[152:153], v[152:153]
	v_mov_b32_e32 v196, v172
	v_mov_b32_e32 v200, v188
	v_mov_b32_e32 v201, v197
	v_pk_fma_f32 v[192:193], v[190:191], v[190:191], v[192:193]
	v_and_b32_e32 v199, 0xffff0000, v148
	v_pk_add_f32 v[172:173], v[172:173], v[188:189]
	v_pk_mul_f32 v[188:189], v[196:197], v[200:201]
	v_and_b32_e32 v195, 0xffff0000, v150
	v_mul_f32_e32 v169, v199, v199
	v_mov_b32_e32 v173, v189
	v_pk_add_f32 v[188:189], v[192:193], v[192:193] op_sel:[0,1] op_sel_hi:[1,0]
	v_lshlrev_b32_e32 v194, 16, v150
	v_lshlrev_b32_e32 v150, 16, v151
	v_and_b32_e32 v151, 0xffff0000, v151
	v_mov_b32_e32 v189, v169
	v_mul_f32_e32 v184, v195, v195
	v_lshlrev_b32_e32 v148, 16, v149
	v_and_b32_e32 v149, 0xffff0000, v149
	v_pk_add_f32 v[172:173], v[172:173], v[188:189]
	v_pk_fma_f32 v[188:189], v[194:195], v[194:195], v[184:185] op_sel_hi:[1,1,0]
	v_mul_f32_e32 v184, v151, v151
	v_mul_f32_e32 v186, v148, v148
	v_mul_f32_e32 v198, v149, v149
	v_pk_fma_f32 v[192:193], v[150:151], v[150:151], v[184:185] op_sel_hi:[1,1,0]
	v_mov_b32_e32 v189, v186
	v_mov_b32_e32 v193, v198
	v_pk_add_f32 v[188:189], v[188:189], v[192:193]
	v_mov_b32_e32 v186, v185
	v_pk_add_f32 v[172:173], v[172:173], v[188:189]
	v_mov_b32_e32 v198, v197
	v_add_f32_e32 v169, v172, v173
	ds_bpermute_b32 v172, v129, v169
	s_waitcnt lgkmcnt(0)
	v_add_f32_e32 v169, v169, v172
	ds_bpermute_b32 v172, v164, v169
	s_waitcnt lgkmcnt(0)
	v_add_f32_e32 v169, v169, v172
	ds_bpermute_b32 v172, v165, v169
	s_waitcnt lgkmcnt(0)
	v_add_f32_e32 v169, v169, v172
	ds_bpermute_b32 v172, v166, v169
	s_waitcnt lgkmcnt(0)
	v_add_f32_e32 v169, v169, v172
	ds_bpermute_b32 v172, v167, v169
	s_waitcnt lgkmcnt(0)
	v_add_f32_e32 v169, v169, v172
	ds_bpermute_b32 v172, v168, v169
	s_waitcnt lgkmcnt(0)
	v_add_f32_e32 v169, v169, v172
	v_fmamk_f32 v169, v169, 0x3a000000, v252
	v_mul_f32_e32 v172, 0x4b800000, v169
	v_cmp_gt_f32_e32 vcc, s88, v169
	s_nop 1
	v_cndmask_b32_e32 v169, v169, v172, vcc
	v_rsq_f32_e32 v169, v169
	s_nop 0
	v_mul_f32_e32 v172, 0x45800000, v169
	v_cndmask_b32_e32 v172, v169, v172, vcc
	v_pk_mul_f32 v[170:171], v[172:173], v[170:171] op_sel_hi:[0,1]
	v_pk_mul_f32 v[162:163], v[172:173], v[162:163] op_sel_hi:[0,1]
	s_waitcnt vmcnt(15)
	v_pk_mul_f32 v[92:93], v[92:93], v[170:171]
	v_pk_mul_f32 v[94:95], v[94:95], v[162:163]
	s_waitcnt vmcnt(13)
	v_pk_fma_f32 v[0:1], v[88:89], v[92:93], v[0:1]
	v_mov_b32_e32 v88, v175
	v_mov_b32_e32 v175, v160
	v_pk_fma_f32 v[2:3], v[90:91], v[94:95], v[2:3]
	v_mov_b32_e32 v89, v161
	v_pk_mul_f32 v[90:91], v[172:173], v[174:175] op_sel_hi:[0,1]
	v_pk_mul_f32 v[88:89], v[172:173], v[88:89] op_sel_hi:[0,1]
	v_pk_mul_f32 v[84:85], v[84:85], v[90:91]
	v_pk_mul_f32 v[86:87], v[86:87], v[88:89]
	s_waitcnt vmcnt(12)
	v_pk_fma_f32 v[4:5], v[80:81], v[84:85], v[4:5]
	v_pk_mul_f32 v[80:81], v[172:173], v[158:159] op_sel_hi:[0,1]
	v_pk_fma_f32 v[6:7], v[82:83], v[86:87], v[6:7]
	v_pk_mul_f32 v[82:83], v[172:173], v[182:183] op_sel_hi:[0,1]
	s_waitcnt vmcnt(11)
	v_pk_mul_f32 v[78:79], v[78:79], v[80:81]
	v_pk_mul_f32 v[76:77], v[76:77], v[82:83]
	s_waitcnt vmcnt(9)
	v_pk_fma_f32 v[10:11], v[74:75], v[78:79], v[10:11]
	v_pk_mul_f32 v[74:75], v[186:187], v[172:173] op_sel_hi:[1,0]
	v_pk_fma_f32 v[8:9], v[72:73], v[76:77], v[8:9]
	v_pk_mul_f32 v[72:73], v[156:157], v[172:173] op_sel_hi:[1,0]
	v_pk_mul_f32 v[68:69], v[68:69], v[74:75]
	v_pk_mul_f32 v[70:71], v[70:71], v[72:73]
	s_waitcnt vmcnt(8)
	v_pk_fma_f32 v[12:13], v[64:65], v[68:69], v[12:13]
	v_mov_b32_e32 v64, v181
	v_mov_b32_e32 v181, v154
	v_pk_fma_f32 v[14:15], v[66:67], v[70:71], v[14:15]
	v_pk_mul_f32 v[66:67], v[172:173], v[180:181] op_sel_hi:[0,1]
	s_waitcnt vmcnt(7)
	v_pk_mul_f32 v[60:61], v[60:61], v[66:67]
	v_mov_b32_e32 v65, v155
	s_waitcnt vmcnt(5)
	v_pk_fma_f32 v[16:17], v[56:57], v[60:61], v[16:17]
	v_mov_b32_e32 v56, v191
	v_mov_b32_e32 v57, v153
	v_pk_mul_f32 v[56:57], v[172:173], v[56:57] op_sel_hi:[0,1]
	v_pk_mul_f32 v[54:55], v[54:55], v[56:57]
	v_pk_mul_f32 v[64:65], v[172:173], v[64:65] op_sel_hi:[0,1]
	s_waitcnt vmcnt(4)
	v_pk_fma_f32 v[22:23], v[50:51], v[54:55], v[22:23]
	v_pk_mul_f32 v[50:51], v[172:173], v[194:195] op_sel_hi:[0,1]
	v_pk_mul_f32 v[62:63], v[62:63], v[64:65]
	v_mov_b32_e32 v191, v152
	s_waitcnt vmcnt(3)
	v_pk_mul_f32 v[44:45], v[44:45], v[50:51]
	v_pk_fma_f32 v[18:19], v[58:59], v[62:63], v[18:19]
	v_pk_mul_f32 v[58:59], v[172:173], v[190:191] op_sel_hi:[0,1]
	s_waitcnt vmcnt(1)
	v_pk_fma_f32 v[24:25], v[40:41], v[44:45], v[24:25]
	v_pk_mul_f32 v[40:41], v[148:149], v[172:173] op_sel_hi:[1,0]
	v_pk_mul_f32 v[52:53], v[52:53], v[58:59]
	v_pk_mul_f32 v[38:39], v[38:39], v[40:41]
	v_pk_fma_f32 v[20:21], v[48:49], v[52:53], v[20:21]
	v_pk_mul_f32 v[48:49], v[172:173], v[150:151] op_sel_hi:[0,1]
	s_waitcnt vmcnt(0)
	v_pk_fma_f32 v[30:31], v[34:35], v[38:39], v[30:31]
	v_pk_mul_f32 v[46:47], v[46:47], v[48:49]
	v_pk_fma_f32 v[26:27], v[42:43], v[46:47], v[26:27]
	v_pk_mul_f32 v[42:43], v[198:199], v[172:173] op_sel_hi:[1,0]
	v_pk_mul_f32 v[36:37], v[36:37], v[42:43]
	v_cvt_pk_bf16_f32 v34, v0, v1
	v_pk_fma_f32 v[28:29], v[32:33], v[36:37], v[28:29]
	v_lshl_add_u64 v[32:33], v[98:99], 0, s[12:13]
	v_cvt_pk_bf16_f32 v35, v2, v3
	global_store_dwordx2 v[32:33], v[34:35], off
	v_cvt_pk_bf16_f32 v34, v4, v5
	v_cvt_pk_bf16_f32 v35, v6, v7
	global_store_dwordx2 v[32:33], v[34:35], off offset:512
	v_cvt_pk_bf16_f32 v34, v8, v9
	v_cvt_pk_bf16_f32 v35, v10, v11
	global_store_dwordx2 v[32:33], v[34:35], off offset:1024
	v_cvt_pk_bf16_f32 v34, v12, v13
	v_cvt_pk_bf16_f32 v35, v14, v15
	global_store_dwordx2 v[32:33], v[34:35], off offset:1536
	v_cvt_pk_bf16_f32 v34, v16, v17
	v_cvt_pk_bf16_f32 v35, v18, v19
	global_store_dwordx2 v[32:33], v[34:35], off offset:2048
	v_cvt_pk_bf16_f32 v34, v20, v21
	v_cvt_pk_bf16_f32 v35, v22, v23
	global_store_dwordx2 v[32:33], v[34:35], off offset:2560
	v_cvt_pk_bf16_f32 v34, v24, v25
	v_cvt_pk_bf16_f32 v35, v26, v27
	global_store_dwordx2 v[32:33], v[34:35], off offset:3072
	v_cvt_pk_bf16_f32 v34, v28, v29
	v_cvt_pk_bf16_f32 v35, v30, v31
	global_store_dwordx2 v[32:33], v[34:35], off offset:3584
	v_mad_i64_i32 v[32:33], s[16:17], s14, v224, v[126:127]
	v_mad_i64_i32 v[34:35], s[14:15], s14, v224, v[130:131]
	s_movk_i32 s14, 0x1000
	global_load_dwordx4 v[68:71], v[102:103], off
	global_load_dwordx4 v[72:75], v[102:103], off offset:1024
	global_load_dwordx4 v[76:79], v[32:33], off
	global_load_dwordx4 v[80:83], v[32:33], off offset:1024
	global_load_dwordx4 v[84:87], v[34:35], off
	global_load_dwordx4 v[88:91], v[34:35], off offset:1024
	global_load_dwordx4 v[92:95], v[102:103], off offset:2048
	global_load_dwordx4 v[148:151], v[102:103], off offset:3072
	global_load_dwordx4 v[152:155], v[32:33], off offset:2048
	global_load_dwordx4 v[156:159], v[32:33], off offset:3072
	global_load_dwordx4 v[160:163], v[34:35], off offset:2048
	global_load_dwordx4 v[170:173], v[34:35], off offset:3072
	v_add_co_u32_e32 v32, vcc, s14, v32
	s_nop 1
	v_addc_co_u32_e32 v33, vcc, 0, v33, vcc
	v_add_co_u32_e32 v34, vcc, s14, v34
	s_nop 1
	v_addc_co_u32_e32 v35, vcc, 0, v35, vcc
	global_load_dwordx4 v[180:183], v[114:115], off
	global_load_dwordx4 v[64:67], v[116:117], off
	global_load_dwordx4 v[184:187], v[32:33], off
	global_load_dwordx4 v[60:63], v[32:33], off offset:1024
	global_load_dwordx4 v[188:191], v[34:35], off
	global_load_dwordx4 v[56:59], v[34:35], off offset:1024
	global_load_dwordx4 v[48:51], v[118:119], off
	global_load_dwordx4 v[40:43], v[120:121], off
	global_load_dwordx4 v[52:55], v[32:33], off offset:2048
	global_load_dwordx4 v[36:39], v[32:33], off offset:3072
	global_load_dwordx4 v[44:47], v[34:35], off offset:2048
	s_nop 0
	global_load_dwordx4 v[32:35], v[34:35], off offset:3072
	v_mov_b32_e32 v192, v1
	v_mov_b32_e32 v193, v5
	v_mov_b32_e32 v174, v0
	v_mov_b32_e32 v175, v4
	v_pk_mul_f32 v[192:193], v[192:193], v[192:193]
	v_mov_b32_e32 v194, v3
	v_mov_b32_e32 v195, v7
	v_pk_fma_f32 v[174:175], v[174:175], v[174:175], v[192:193]
	v_mov_b32_e32 v192, v2
	v_mov_b32_e32 v193, v6
	v_pk_mul_f32 v[194:195], v[194:195], v[194:195]
	s_waitcnt vmcnt(21)
	v_pk_add_f32 v[76:77], v[76:77], 1.0 op_sel_hi:[1,0]
	v_pk_fma_f32 v[192:193], v[192:193], v[192:193], v[194:195]
	v_pk_mul_f32 v[194:195], v[8:9], v[8:9]
	v_pk_add_f32 v[174:175], v[174:175], v[192:193]
	v_pk_mul_f32 v[192:193], v[10:11], v[10:11]
	v_pk_add_f32 v[174:175], v[174:175], v[174:175] op_sel_hi:[0,1]
	v_pk_mov_b32 v[196:197], v[194:195], v[192:193] op_sel:[1,0]
	v_mov_b32_e32 v195, v193
	v_mul_f32_e32 v174, v12, v12
	v_pk_add_f32 v[192:193], v[196:197], v[194:195]
	v_pk_fma_f32 v[194:195], v[12:13], v[12:13], v[174:175] op_sel_hi:[1,1,0]
	v_mul_f32_e32 v174, v14, v14
	v_pk_add_f32 v[192:193], v[192:193], v[192:193] op_sel_hi:[0,1]
	v_pk_fma_f32 v[196:197], v[14:15], v[14:15], v[174:175] op_sel_hi:[1,1,0]
	v_mul_f32_e32 v194, v16, v16
	v_mul_f32_e32 v196, v17, v17
	v_mul_f32_e32 v192, v18, v18
	v_mul_f32_e32 v174, v19, v19
	v_pk_add_f32 v[194:195], v[194:195], v[196:197]
	v_pk_add_f32 v[174:175], v[192:193], v[174:175]
	v_pk_mul_f32 v[192:193], v[22:23], v[22:23]
	v_pk_add_f32 v[174:175], v[194:195], v[174:175]
	v_pk_mul_f32 v[194:195], v[20:21], v[20:21]
	v_pk_add_f32 v[174:175], v[174:175], v[174:175] op_sel_hi:[0,1]
	v_pk_mov_b32 v[196:197], v[194:195], v[192:193] op_sel:[1,0]
	v_mov_b32_e32 v195, v193
	v_mul_f32_e32 v174, v24, v24
	v_pk_add_f32 v[192:193], v[196:197], v[194:195]
	v_pk_fma_f32 v[194:195], v[24:25], v[24:25], v[174:175] op_sel_hi:[1,1,0]
	v_mul_f32_e32 v174, v26, v26
	v_pk_add_f32 v[192:193], v[192:193], v[192:193] op_sel_hi:[0,1]
	v_pk_fma_f32 v[196:197], v[26:27], v[26:27], v[174:175] op_sel_hi:[1,1,0]
	v_mul_f32_e32 v194, v28, v28
	v_mul_f32_e32 v196, v29, v29
	v_mul_f32_e32 v192, v30, v30
	v_mul_f32_e32 v174, v31, v31
	v_pk_add_f32 v[194:195], v[194:195], v[196:197]
	v_pk_add_f32 v[174:175], v[192:193], v[174:175]
	v_pk_add_f32 v[78:79], v[78:79], 1.0 op_sel_hi:[1,0]
	v_pk_add_f32 v[174:175], v[194:195], v[174:175]
	v_lshl_add_u64 v[192:193], v[104:105], 0, s[12:13]
	v_add_f32_e32 v169, v174, v175
	ds_bpermute_b32 v174, v129, v169
	s_waitcnt vmcnt(8)
	v_pk_add_f32 v[60:61], v[60:61], 1.0 op_sel_hi:[1,0]
	v_pk_add_f32 v[62:63], v[62:63], 1.0 op_sel_hi:[1,0]
	s_waitcnt vmcnt(3)
	v_pk_add_f32 v[52:53], v[52:53], 1.0 op_sel_hi:[1,0]
	v_pk_add_f32 v[54:55], v[54:55], 1.0 op_sel_hi:[1,0]
	s_waitcnt lgkmcnt(0)
	v_add_f32_e32 v169, v169, v174
	ds_bpermute_b32 v174, v164, v169
	s_waitcnt vmcnt(2)
	v_pk_add_f32 v[36:37], v[36:37], 1.0 op_sel_hi:[1,0]
	v_pk_add_f32 v[38:39], v[38:39], 1.0 op_sel_hi:[1,0]
	v_readlane_b32 s12, v254, 11
	v_readlane_b32 s13, v254, 12
	s_waitcnt lgkmcnt(0)
	v_add_f32_e32 v169, v169, v174
	ds_bpermute_b32 v174, v165, v169
	s_add_u32 s24, s24, s12
	s_addc_u32 s25, s25, s13
	v_readlane_b32 s12, v254, 9
	v_readlane_b32 s13, v254, 10
	s_waitcnt lgkmcnt(0)
	v_add_f32_e32 v169, v169, v174
	ds_bpermute_b32 v174, v166, v169
	s_add_u32 s10, s10, s12
	s_addc_u32 s11, s11, s13
	s_cmpk_gt_i32 s24, 0x3fff
	s_waitcnt lgkmcnt(0)
	v_add_f32_e32 v169, v169, v174
	ds_bpermute_b32 v174, v167, v169
	s_waitcnt lgkmcnt(0)
	v_add_f32_e32 v169, v169, v174
	ds_bpermute_b32 v174, v168, v169
	s_waitcnt lgkmcnt(0)
	v_add_f32_e32 v169, v169, v174
	v_fmamk_f32 v169, v169, 0x3a000000, v252
	v_mul_f32_e32 v174, 0x4b800000, v169
	v_cmp_gt_f32_e32 vcc, s88, v169
	s_nop 1
	v_cndmask_b32_e32 v169, v169, v174, vcc
	v_rsq_f32_e32 v169, v169
	s_nop 0
	v_mul_f32_e32 v174, 0x45800000, v169
	v_cndmask_b32_e32 v174, v169, v174, vcc
	v_pk_mul_f32 v[196:197], v[0:1], v[174:175] op_sel_hi:[1,0]
	v_pk_mul_f32 v[194:195], v[2:3], v[174:175] op_sel_hi:[1,0]
	v_pk_mul_f32 v[68:69], v[68:69], v[196:197]
	v_pk_mul_f32 v[70:71], v[70:71], v[194:195]
	v_pk_fma_f32 v[68:69], v[76:77], v[68:69], v[84:85]
	v_pk_fma_f32 v[70:71], v[78:79], v[70:71], v[86:87]
	v_bfe_u32 v76, v68, 16, 1
	v_add3_u32 v68, v68, v76, s65
	v_bfe_u32 v76, v69, 16, 1
	v_lshrrev_b32_e32 v68, 16, v68
	v_add3_u32 v69, v69, v76, s65
	v_and_or_b32 v68, v69, s61, v68
	v_cvt_pk_bf16_f32 v69, v70, v71
	global_store_dwordx2 v[192:193], v[68:69], off
	v_pk_mul_f32 v[68:69], v[6:7], v[174:175] op_sel_hi:[1,0]
	v_pk_mul_f32 v[70:71], v[4:5], v[174:175] op_sel_hi:[1,0]
	v_pk_mul_f32 v[68:69], v[74:75], v[68:69]
	v_pk_mul_f32 v[70:71], v[72:73], v[70:71]
	v_pk_add_f32 v[74:75], v[80:81], 1.0 op_sel_hi:[1,0]
	v_pk_add_f32 v[72:73], v[82:83], 1.0 op_sel_hi:[1,0]
	v_pk_fma_f32 v[70:71], v[74:75], v[70:71], v[88:89]
	v_pk_fma_f32 v[68:69], v[72:73], v[68:69], v[90:91]
	v_cvt_pk_bf16_f32 v70, v70, v71
	v_cvt_pk_bf16_f32 v71, v68, v69
	global_store_dwordx2 v[192:193], v[70:71], off offset:512
	v_pk_mul_f32 v[70:71], v[8:9], v[174:175] op_sel_hi:[1,0]
	v_pk_mul_f32 v[68:69], v[10:11], v[174:175] op_sel_hi:[1,0]
	v_pk_mul_f32 v[70:71], v[92:93], v[70:71]
	v_pk_add_f32 v[74:75], v[152:153], 1.0 op_sel_hi:[1,0]
	v_pk_mul_f32 v[68:69], v[94:95], v[68:69]
	v_pk_add_f32 v[72:73], v[154:155], 1.0 op_sel_hi:[1,0]
	v_pk_fma_f32 v[70:71], v[74:75], v[70:71], v[160:161]
	v_pk_fma_f32 v[68:69], v[72:73], v[68:69], v[162:163]
	v_cvt_pk_bf16_f32 v70, v70, v71
	v_cvt_pk_bf16_f32 v71, v68, v69
	global_store_dwordx2 v[192:193], v[70:71], off offset:1024
	v_pk_mul_f32 v[70:71], v[12:13], v[174:175] op_sel_hi:[1,0]
	v_pk_mul_f32 v[68:69], v[14:15], v[174:175] op_sel_hi:[1,0]
	v_pk_mul_f32 v[70:71], v[148:149], v[70:71]
	v_pk_add_f32 v[74:75], v[156:157], 1.0 op_sel_hi:[1,0]
	v_pk_mul_f32 v[68:69], v[150:151], v[68:69]
	v_pk_add_f32 v[72:73], v[158:159], 1.0 op_sel_hi:[1,0]
	v_pk_fma_f32 v[70:71], v[74:75], v[70:71], v[170:171]
	v_pk_fma_f32 v[68:69], v[72:73], v[68:69], v[172:173]
	v_cvt_pk_bf16_f32 v70, v70, v71
	v_cvt_pk_bf16_f32 v71, v68, v69
	global_store_dwordx2 v[192:193], v[70:71], off offset:1536
	v_pk_mul_f32 v[70:71], v[16:17], v[174:175] op_sel_hi:[1,0]
	v_pk_mul_f32 v[68:69], v[18:19], v[174:175] op_sel_hi:[1,0]
	v_pk_mul_f32 v[70:71], v[180:181], v[70:71]
	v_pk_add_f32 v[74:75], v[184:185], 1.0 op_sel_hi:[1,0]
	v_pk_mul_f32 v[68:69], v[182:183], v[68:69]
	v_pk_add_f32 v[72:73], v[186:187], 1.0 op_sel_hi:[1,0]
	v_pk_fma_f32 v[70:71], v[74:75], v[70:71], v[188:189]
	v_pk_fma_f32 v[68:69], v[72:73], v[68:69], v[190:191]
	v_bfe_u32 v72, v70, 16, 1
	v_add3_u32 v70, v70, v72, s65
	v_bfe_u32 v72, v71, 16, 1
	v_lshrrev_b32_e32 v70, 16, v70
	v_add3_u32 v71, v71, v72, s65
	v_and_or_b32 v70, v71, s61, v70
	v_cvt_pk_bf16_f32 v71, v68, v69
	global_store_dwordx2 v[192:193], v[70:71], off offset:2048
	v_pk_mul_f32 v[70:71], v[20:21], v[174:175] op_sel_hi:[1,0]
	v_pk_mul_f32 v[68:69], v[22:23], v[174:175] op_sel_hi:[1,0]
	v_pk_mul_f32 v[64:65], v[64:65], v[70:71]
	v_pk_mul_f32 v[66:67], v[66:67], v[68:69]
	v_pk_fma_f32 v[56:57], v[60:61], v[64:65], v[56:57]
	v_pk_fma_f32 v[58:59], v[62:63], v[66:67], v[58:59]
	v_bfe_u32 v60, v56, 16, 1
	v_add3_u32 v56, v56, v60, s65
	v_bfe_u32 v60, v57, 16, 1
	v_lshrrev_b32_e32 v56, 16, v56
	v_add3_u32 v57, v57, v60, s65
	v_and_or_b32 v56, v57, s61, v56
	v_cvt_pk_bf16_f32 v57, v58, v59
	v_pk_mul_f32 v[58:59], v[24:25], v[174:175] op_sel_hi:[1,0]
	global_store_dwordx2 v[192:193], v[56:57], off offset:2560
	v_pk_mul_f32 v[48:49], v[48:49], v[58:59]
	v_pk_mul_f32 v[56:57], v[26:27], v[174:175] op_sel_hi:[1,0]
	s_waitcnt vmcnt(7)
	v_pk_fma_f32 v[44:45], v[52:53], v[48:49], v[44:45]
	v_pk_mul_f32 v[50:51], v[50:51], v[56:57]
	v_bfe_u32 v48, v44, 16, 1
	v_add3_u32 v44, v44, v48, s65
	v_bfe_u32 v48, v45, 16, 1
	v_pk_fma_f32 v[46:47], v[54:55], v[50:51], v[46:47]
	v_lshrrev_b32_e32 v44, 16, v44
	v_add3_u32 v45, v45, v48, s65
	v_and_or_b32 v44, v45, s61, v44
	v_cvt_pk_bf16_f32 v45, v46, v47
	v_pk_mul_f32 v[46:47], v[28:29], v[174:175] op_sel_hi:[1,0]
	global_store_dwordx2 v[192:193], v[44:45], off offset:3072
	v_pk_mul_f32 v[40:41], v[40:41], v[46:47]
	v_pk_mul_f32 v[44:45], v[30:31], v[174:175] op_sel_hi:[1,0]
	s_waitcnt vmcnt(7)
	v_pk_fma_f32 v[32:33], v[36:37], v[40:41], v[32:33]
	v_pk_mul_f32 v[42:43], v[42:43], v[44:45]
	v_pk_fma_f32 v[34:35], v[38:39], v[42:43], v[34:35]
	v_cvt_pk_bf16_f32 v32, v32, v33
	v_cvt_pk_bf16_f32 v33, v34, v35
	global_store_dwordx2 v[192:193], v[32:33], off offset:3584
	v_mov_b64_e32 v[32:33], v[146:147]
	v_mov_b64_e32 v[34:35], v[144:145]
	v_mov_b64_e32 v[36:37], v[142:143]
	v_mov_b64_e32 v[38:39], v[140:141]
	v_mov_b64_e32 v[40:41], v[138:139]
	v_mov_b64_e32 v[42:43], v[136:137]
	v_mov_b64_e32 v[44:45], v[134:135]
	v_mov_b64_e32 v[46:47], v[132:133]
	s_cbranch_scc1 .LBB0_939

.LBB0_1209:
	v_cvt_pk_bf16_f32 v192, v124, v125
	s_mov_b64 s[24:25], 0x4b400000
	v_lshl_add_u64 v[172:173], v[164:165], 0, s[24:25]
	v_cvt_pk_bf16_f32 v193, v126, v127
	global_store_dwordx2 v[172:173], v[192:193], off
	v_cvt_pk_bf16_f32 v172, v120, v121
	s_mov_b64 s[24:25], 0x4b400200
	v_lshl_add_u64 v[174:175], v[164:165], 0, s[24:25]
	v_cvt_pk_bf16_f32 v173, v122, v123
	global_store_dwordx2 v[174:175], v[172:173], off
	v_cvt_pk_bf16_f32 v172, v116, v117
	s_mov_b64 s[24:25], 0x4b400400
	v_lshl_add_u64 v[180:181], v[164:165], 0, s[24:25]
	v_cvt_pk_bf16_f32 v173, v118, v119
	global_store_dwordx2 v[180:181], v[172:173], off
	v_cvt_pk_bf16_f32 v172, v112, v113
	s_mov_b64 s[24:25], 0x4b400600
	v_lshl_add_u64 v[182:183], v[164:165], 0, s[24:25]
	v_cvt_pk_bf16_f32 v173, v114, v115
	global_store_dwordx2 v[182:183], v[172:173], off
	v_cvt_pk_bf16_f32 v172, v108, v109
	s_mov_b64 s[24:25], 0x4b400800
	v_lshl_add_u64 v[184:185], v[164:165], 0, s[24:25]
	v_cvt_pk_bf16_f32 v173, v110, v111
	global_store_dwordx2 v[184:185], v[172:173], off
	v_cvt_pk_bf16_f32 v172, v104, v105
	s_mov_b64 s[24:25], 0x4b400a00
	v_lshl_add_u64 v[186:187], v[164:165], 0, s[24:25]
	v_cvt_pk_bf16_f32 v173, v106, v107
	global_store_dwordx2 v[186:187], v[172:173], off
	v_cvt_pk_bf16_f32 v172, v100, v101
	s_mov_b64 s[24:25], 0x4b400c00
	v_lshl_add_u64 v[188:189], v[164:165], 0, s[24:25]
	v_cvt_pk_bf16_f32 v173, v102, v103
	global_store_dwordx2 v[188:189], v[172:173], off
	v_cvt_pk_bf16_f32 v172, v96, v97
	v_bfe_u32 v171, v98, 16, 1
	v_add3_u32 v171, v98, v171, s65
	v_bfe_u32 v173, v99, 16, 1
	s_mov_b64 s[24:25], 0x4b400e00
	v_lshrrev_b32_e32 v171, 16, v171
	v_add3_u32 v173, v99, v173, s65
	v_lshl_add_u64 v[190:191], v[164:165], 0, s[24:25]
	v_and_or_b32 v173, v173, s61, v171
	global_store_dwordx2 v[190:191], v[172:173], off
	s_cbranch_execnz .LBB0_1208

.LBB0_1211:
	v_mov_b32_e32 v174, v125
	v_mov_b32_e32 v175, v121
	v_mov_b32_e32 v172, v124
	v_mov_b32_e32 v173, v120
	v_pk_mul_f32 v[174:175], v[174:175], v[174:175]
	v_mov_b32_e32 v180, v127
	v_mov_b32_e32 v181, v123
	v_pk_fma_f32 v[172:173], v[172:173], v[172:173], v[174:175]
	v_mov_b32_e32 v174, v126
	v_mov_b32_e32 v175, v122
	v_pk_mul_f32 v[180:181], v[180:181], v[180:181]
	s_mov_b32 s24, 0x17800000
	v_pk_fma_f32 v[174:175], v[174:175], v[174:175], v[180:181]
	v_pk_mul_f32 v[180:181], v[116:117], v[116:117]
	v_pk_add_f32 v[172:173], v[172:173], v[174:175]
	v_pk_mul_f32 v[174:175], v[118:119], v[118:119]
	v_pk_add_f32 v[172:173], v[172:173], v[172:173] op_sel_hi:[0,1]
	v_pk_mov_b32 v[182:183], v[180:181], v[174:175] op_sel:[1,0]
	v_mov_b32_e32 v181, v175
	v_mul_f32_e32 v172, v112, v112
	v_pk_add_f32 v[174:175], v[182:183], v[180:181]
	v_pk_fma_f32 v[180:181], v[112:113], v[112:113], v[172:173] op_sel_hi:[1,1,0]
	v_mul_f32_e32 v172, v114, v114
	v_pk_add_f32 v[174:175], v[174:175], v[174:175] op_sel_hi:[0,1]
	v_pk_fma_f32 v[182:183], v[114:115], v[114:115], v[172:173] op_sel_hi:[1,1,0]
	v_mul_f32_e32 v180, v108, v108
	v_mul_f32_e32 v182, v109, v109
	v_mul_f32_e32 v174, v110, v110
	v_mul_f32_e32 v172, v111, v111
	v_pk_add_f32 v[180:181], v[180:181], v[182:183]
	v_pk_add_f32 v[172:173], v[174:175], v[172:173]
	v_pk_mul_f32 v[174:175], v[106:107], v[106:107]
	v_pk_add_f32 v[172:173], v[180:181], v[172:173]
	v_pk_mul_f32 v[180:181], v[104:105], v[104:105]
	v_pk_add_f32 v[172:173], v[172:173], v[172:173] op_sel_hi:[0,1]
	v_pk_mov_b32 v[182:183], v[180:181], v[174:175] op_sel:[1,0]
	v_mov_b32_e32 v181, v175
	v_mul_f32_e32 v172, v100, v100
	v_pk_add_f32 v[174:175], v[182:183], v[180:181]
	v_pk_fma_f32 v[180:181], v[100:101], v[100:101], v[172:173] op_sel_hi:[1,1,0]
	v_mul_f32_e32 v172, v102, v102
	v_pk_add_f32 v[174:175], v[174:175], v[174:175] op_sel_hi:[0,1]
	v_pk_fma_f32 v[182:183], v[102:103], v[102:103], v[172:173] op_sel_hi:[1,1,0]
	v_mul_f32_e32 v180, v96, v96
	v_mul_f32_e32 v182, v97, v97
	v_mul_f32_e32 v174, v98, v98
	v_mul_f32_e32 v172, v99, v99
	v_pk_add_f32 v[180:181], v[180:181], v[182:183]
	v_pk_add_f32 v[172:173], v[174:175], v[172:173]
	s_nop 0
	v_pk_add_f32 v[172:173], v[180:181], v[172:173]
	s_nop 0
	v_add_f32_e32 v171, v172, v173
	ds_bpermute_b32 v172, v129, v171
	s_waitcnt lgkmcnt(0)
	v_add_f32_e32 v171, v171, v172
	ds_bpermute_b32 v172, v166, v171
	s_waitcnt lgkmcnt(0)
	v_add_f32_e32 v171, v171, v172
	ds_bpermute_b32 v172, v167, v171
	s_waitcnt lgkmcnt(0)
	v_add_f32_e32 v171, v171, v172
	ds_bpermute_b32 v172, v168, v171
	s_waitcnt lgkmcnt(0)
	v_add_f32_e32 v171, v171, v172
	ds_bpermute_b32 v172, v169, v171
	s_waitcnt lgkmcnt(0)
	v_add_f32_e32 v171, v171, v172
	ds_bpermute_b32 v172, v170, v171
	s_waitcnt lgkmcnt(0)
	v_add_f32_e32 v171, v171, v172
	v_fmamk_f32 v171, v171, 0x3a000000, v252
	v_mul_f32_e32 v172, 0x4b800000, v171
	v_cmp_gt_f32_e32 vcc, s88, v171
	s_nop 1
	v_cndmask_b32_e32 v171, v171, v172, vcc
	v_rsq_f32_e32 v171, v171
	s_nop 0
	v_mul_f32_e32 v172, 0x45800000, v171
	v_cndmask_b32_e32 v172, v171, v172, vcc
	v_pk_mul_f32 v[124:125], v[124:125], v[172:173] op_sel_hi:[1,0]
	v_pk_mul_f32 v[126:127], v[126:127], v[172:173] op_sel_hi:[1,0]
	v_pk_fma_f32 v[124:125], v[130:131], v[124:125], v[64:65]
	v_pk_fma_f32 v[126:127], v[132:133], v[126:127], v[66:67]
	v_bfe_u32 v171, v124, 16, 1
	v_add3_u32 v124, v124, v171, s65
	v_bfe_u32 v171, v125, 16, 1
	v_lshrrev_b32_e32 v124, 16, v124
	v_add3_u32 v125, v125, v171, s65
	v_and_or_b32 v124, v125, s61, v124
	s_nop 0
	s_nop 0
	s_nop 0
	v_cvt_pk_bf16_f32 v125, v126, v127
	v_add_co_u32_e32 v126, vcc, s24, v164
	v_pk_mul_f32 v[120:121], v[120:121], v[172:173] op_sel_hi:[1,0]
	s_nop 0
	v_addc_co_u32_e32 v127, vcc, 0, v165, vcc
	v_pk_fma_f32 v[120:121], v[134:135], v[120:121], v[68:69]
	global_store_dwordx2 v[126:127], v[124:125], off
	v_bfe_u32 v124, v120, 16, 1
	v_pk_mul_f32 v[122:123], v[122:123], v[172:173] op_sel_hi:[1,0]
	v_add3_u32 v120, v120, v124, s65
	v_bfe_u32 v124, v121, 16, 1
	v_pk_fma_f32 v[122:123], v[136:137], v[122:123], v[70:71]
	v_lshrrev_b32_e32 v120, 16, v120
	v_add3_u32 v121, v121, v124, s65
	v_and_or_b32 v120, v121, s61, v120
	v_bfe_u32 v121, v122, 16, 1
	v_add3_u32 v121, v122, v121, s65
	v_bfe_u32 v122, v123, 16, 1
	v_lshrrev_b32_e32 v121, 16, v121
	v_add3_u32 v122, v123, v122, s65
	v_pk_mul_f32 v[116:117], v[116:117], v[172:173] op_sel_hi:[1,0]
	v_and_or_b32 v121, v122, s61, v121
	v_pk_fma_f32 v[116:117], v[138:139], v[116:117], v[72:73]
	global_store_dwordx2 v[126:127], v[120:121], off offset:512
	v_bfe_u32 v120, v116, 16, 1
	v_pk_mul_f32 v[118:119], v[118:119], v[172:173] op_sel_hi:[1,0]
	v_add3_u32 v116, v116, v120, s65
	v_bfe_u32 v120, v117, 16, 1
	v_pk_fma_f32 v[118:119], v[140:141], v[118:119], v[74:75]
	v_lshrrev_b32_e32 v116, 16, v116
	v_add3_u32 v117, v117, v120, s65
	v_and_or_b32 v116, v117, s61, v116
	v_bfe_u32 v117, v118, 16, 1
	v_add3_u32 v117, v118, v117, s65
	v_bfe_u32 v118, v119, 16, 1
	v_lshrrev_b32_e32 v117, 16, v117
	v_add3_u32 v118, v119, v118, s65
	v_pk_mul_f32 v[112:113], v[112:113], v[172:173] op_sel_hi:[1,0]
	v_and_or_b32 v117, v118, s61, v117
	v_pk_fma_f32 v[112:113], v[142:143], v[112:113], v[76:77]
	global_store_dwordx2 v[126:127], v[116:117], off offset:1024
	v_bfe_u32 v116, v112, 16, 1
	v_pk_mul_f32 v[114:115], v[114:115], v[172:173] op_sel_hi:[1,0]
	v_add3_u32 v112, v112, v116, s65
	v_bfe_u32 v116, v113, 16, 1
	v_pk_fma_f32 v[114:115], v[144:145], v[114:115], v[78:79]
	v_lshrrev_b32_e32 v112, 16, v112
	v_add3_u32 v113, v113, v116, s65
	v_and_or_b32 v112, v113, s61, v112
	v_bfe_u32 v113, v114, 16, 1
	v_add3_u32 v113, v114, v113, s65
	v_bfe_u32 v114, v115, 16, 1
	v_lshrrev_b32_e32 v113, 16, v113
	v_add3_u32 v114, v115, v114, s65
	v_pk_mul_f32 v[108:109], v[108:109], v[172:173] op_sel_hi:[1,0]
	v_and_or_b32 v113, v114, s61, v113
	v_pk_fma_f32 v[108:109], v[146:147], v[108:109], v[80:81]
	global_store_dwordx2 v[126:127], v[112:113], off offset:1536
	v_bfe_u32 v112, v108, 16, 1
	v_pk_mul_f32 v[110:111], v[110:111], v[172:173] op_sel_hi:[1,0]
	v_add3_u32 v108, v108, v112, s65
	v_bfe_u32 v112, v109, 16, 1
	v_pk_fma_f32 v[110:111], v[148:149], v[110:111], v[82:83]
	v_lshrrev_b32_e32 v108, 16, v108
	v_add3_u32 v109, v109, v112, s65
	v_and_or_b32 v108, v109, s61, v108
	v_bfe_u32 v109, v110, 16, 1
	v_add3_u32 v109, v110, v109, s65
	v_bfe_u32 v110, v111, 16, 1
	v_lshrrev_b32_e32 v109, 16, v109
	v_add3_u32 v110, v111, v110, s65
	v_pk_mul_f32 v[104:105], v[104:105], v[172:173] op_sel_hi:[1,0]
	v_and_or_b32 v109, v110, s61, v109
	v_pk_fma_f32 v[104:105], v[150:151], v[104:105], v[84:85]
	global_store_dwordx2 v[126:127], v[108:109], off offset:2048
	v_bfe_u32 v108, v104, 16, 1
	v_pk_mul_f32 v[106:107], v[106:107], v[172:173] op_sel_hi:[1,0]
	v_add3_u32 v104, v104, v108, s65
	v_bfe_u32 v108, v105, 16, 1
	v_pk_fma_f32 v[106:107], v[152:153], v[106:107], v[86:87]
	v_lshrrev_b32_e32 v104, 16, v104
	v_add3_u32 v105, v105, v108, s65
	v_and_or_b32 v104, v105, s61, v104
	v_bfe_u32 v105, v106, 16, 1
	v_add3_u32 v105, v106, v105, s65
	v_bfe_u32 v106, v107, 16, 1
	v_lshrrev_b32_e32 v105, 16, v105
	v_add3_u32 v106, v107, v106, s65
	v_pk_mul_f32 v[100:101], v[100:101], v[172:173] op_sel_hi:[1,0]
	v_and_or_b32 v105, v106, s61, v105
	v_pk_fma_f32 v[100:101], v[154:155], v[100:101], v[88:89]
	global_store_dwordx2 v[126:127], v[104:105], off offset:2560
	v_bfe_u32 v104, v100, 16, 1
	v_pk_mul_f32 v[102:103], v[102:103], v[172:173] op_sel_hi:[1,0]
	v_add3_u32 v100, v100, v104, s65
	v_bfe_u32 v104, v101, 16, 1
	v_pk_fma_f32 v[102:103], v[156:157], v[102:103], v[90:91]
	v_lshrrev_b32_e32 v100, 16, v100
	v_add3_u32 v101, v101, v104, s65
	v_and_or_b32 v100, v101, s61, v100
	v_bfe_u32 v101, v102, 16, 1
	v_add3_u32 v101, v102, v101, s65
	v_bfe_u32 v102, v103, 16, 1
	v_lshrrev_b32_e32 v101, 16, v101
	v_add3_u32 v102, v103, v102, s65
	v_pk_mul_f32 v[96:97], v[96:97], v[172:173] op_sel_hi:[1,0]
	v_and_or_b32 v101, v102, s61, v101
	v_pk_fma_f32 v[96:97], v[158:159], v[96:97], v[92:93]
	global_store_dwordx2 v[126:127], v[100:101], off offset:3072
	v_bfe_u32 v100, v96, 16, 1
	v_pk_mul_f32 v[98:99], v[98:99], v[172:173] op_sel_hi:[1,0]
	v_add3_u32 v96, v96, v100, s65
	v_bfe_u32 v100, v97, 16, 1
	v_pk_fma_f32 v[98:99], v[160:161], v[98:99], v[94:95]
	v_lshrrev_b32_e32 v96, 16, v96
	v_add3_u32 v97, v97, v100, s65
	v_and_or_b32 v96, v97, s61, v96
	v_bfe_u32 v97, v98, 16, 1
	v_add3_u32 v97, v98, v97, s65
	v_bfe_u32 v98, v99, 16, 1
	v_lshrrev_b32_e32 v97, 16, v97
	v_add3_u32 v98, v99, v98, s65
	v_and_or_b32 v97, v98, s61, v97
	global_store_dwordx2 v[126:127], v[96:97], off offset:3584
	s_branch .LBB0_1205

.LBB0_1220:
	v_cvt_pk_bf16_f32 v48, v28, v29
	v_bfe_u32 v49, v30, 16, 1
	v_add3_u32 v49, v30, v49, s65
	v_bfe_u32 v50, v31, 16, 1
	s_mov_b64 s[10:11], 0x4b400000
	v_lshrrev_b32_e32 v49, 16, v49
	v_add3_u32 v50, v31, v50, s65
	v_lshl_add_u64 v[32:33], v[108:109], 0, s[10:11]
	v_and_or_b32 v49, v50, s61, v49
	global_store_dwordx2 v[32:33], v[48:49], off
	v_cvt_pk_bf16_f32 v32, v24, v25
	v_bfe_u32 v33, v26, 16, 1
	v_add3_u32 v33, v26, v33, s65
	v_bfe_u32 v48, v27, 16, 1
	s_mov_b64 s[10:11], 0x4b400200
	v_lshrrev_b32_e32 v33, 16, v33
	v_add3_u32 v48, v27, v48, s65
	v_lshl_add_u64 v[34:35], v[108:109], 0, s[10:11]
	v_and_or_b32 v33, v48, s61, v33
	global_store_dwordx2 v[34:35], v[32:33], off
	v_cvt_pk_bf16_f32 v32, v20, v21
	s_mov_b64 s[10:11], 0x4b400400
	v_lshl_add_u64 v[36:37], v[108:109], 0, s[10:11]
	v_cvt_pk_bf16_f32 v33, v22, v23
	global_store_dwordx2 v[36:37], v[32:33], off
	v_cvt_pk_bf16_f32 v32, v16, v17
	s_mov_b64 s[10:11], 0x4b400600
	v_lshl_add_u64 v[38:39], v[108:109], 0, s[10:11]
	v_cvt_pk_bf16_f32 v33, v18, v19
	global_store_dwordx2 v[38:39], v[32:33], off
	v_cvt_pk_bf16_f32 v32, v12, v13
	s_mov_b64 s[10:11], 0x4b400800
	v_lshl_add_u64 v[40:41], v[108:109], 0, s[10:11]
	v_cvt_pk_bf16_f32 v33, v14, v15
	global_store_dwordx2 v[40:41], v[32:33], off
	v_cvt_pk_bf16_f32 v32, v8, v9
	s_mov_b64 s[10:11], 0x4b400a00
	v_lshl_add_u64 v[42:43], v[108:109], 0, s[10:11]
	v_cvt_pk_bf16_f32 v33, v10, v11
	global_store_dwordx2 v[42:43], v[32:33], off
	v_cvt_pk_bf16_f32 v32, v4, v5
	s_mov_b64 s[10:11], 0x4b400c00
	v_lshl_add_u64 v[44:45], v[108:109], 0, s[10:11]
	v_cvt_pk_bf16_f32 v33, v6, v7
	global_store_dwordx2 v[44:45], v[32:33], off
	v_cvt_pk_bf16_f32 v32, v0, v1
	v_bfe_u32 v33, v2, 16, 1
	v_add3_u32 v33, v2, v33, s65
	v_bfe_u32 v34, v3, 16, 1
	s_mov_b64 s[10:11], 0x4b400e00
	v_lshrrev_b32_e32 v33, 16, v33
	v_add3_u32 v34, v3, v34, s65
	v_lshl_add_u64 v[46:47], v[108:109], 0, s[10:11]
	v_and_or_b32 v33, v34, s61, v33
	global_store_dwordx2 v[46:47], v[32:33], off
	s_cbranch_execnz .LBB0_1219

.LBB0_1222:
	v_mad_i64_i32 v[32:33], s[10:11], s12, v224, v[102:103]
	v_mad_i64_i32 v[34:35], s[10:11], s12, v224, v[104:105]
	s_movk_i32 s10, 0x1000
	global_load_dwordx4 v[116:119], v[82:83], off
	global_load_dwordx4 v[120:123], v[82:83], off offset:1024
	global_load_dwordx4 v[124:127], v[32:33], off
	global_load_dwordx4 v[128:131], v[32:33], off offset:1024
	global_load_dwordx4 v[132:135], v[34:35], off
	global_load_dwordx4 v[136:139], v[34:35], off offset:1024
	global_load_dwordx4 v[140:143], v[82:83], off offset:2048
	global_load_dwordx4 v[144:147], v[82:83], off offset:3072
	global_load_dwordx4 v[148:151], v[32:33], off offset:2048
	global_load_dwordx4 v[152:155], v[32:33], off offset:3072
	global_load_dwordx4 v[156:159], v[34:35], off offset:2048
	global_load_dwordx4 v[160:163], v[34:35], off offset:3072
	v_add_co_u32_e32 v32, vcc, s10, v32
	s_nop 1
	v_addc_co_u32_e32 v33, vcc, 0, v33, vcc
	v_add_co_u32_e32 v34, vcc, s10, v34
	s_nop 1
	v_addc_co_u32_e32 v35, vcc, 0, v35, vcc
	global_load_dwordx4 v[72:75], v[92:93], off
	global_load_dwordx4 v[64:67], v[94:95], off
	global_load_dwordx4 v[76:79], v[32:33], off
	global_load_dwordx4 v[60:63], v[32:33], off offset:1024
	global_load_dwordx4 v[68:71], v[34:35], off
	global_load_dwordx4 v[56:59], v[34:35], off offset:1024
	global_load_dwordx4 v[48:51], v[96:97], off
	global_load_dwordx4 v[40:43], v[98:99], off
	global_load_dwordx4 v[52:55], v[32:33], off offset:2048
	global_load_dwordx4 v[36:39], v[32:33], off offset:3072
	global_load_dwordx4 v[44:47], v[34:35], off offset:2048
	s_nop 0
	global_load_dwordx4 v[32:35], v[34:35], off offset:3072
	v_mov_b32_e32 v166, v29
	v_mov_b32_e32 v167, v25
	v_mov_b32_e32 v164, v28
	v_mov_b32_e32 v165, v24
	v_pk_mul_f32 v[166:167], v[166:167], v[166:167]
	v_mov_b32_e32 v168, v31
	v_mov_b32_e32 v169, v27
	v_pk_fma_f32 v[164:165], v[164:165], v[164:165], v[166:167]
	v_mov_b32_e32 v166, v30
	v_mov_b32_e32 v167, v26
	v_pk_mul_f32 v[168:169], v[168:169], v[168:169]
	s_mov_b32 s10, 0x17800000
	v_pk_fma_f32 v[166:167], v[166:167], v[166:167], v[168:169]
	v_pk_mul_f32 v[168:169], v[20:21], v[20:21]
	v_pk_add_f32 v[164:165], v[164:165], v[166:167]
	v_pk_mul_f32 v[166:167], v[22:23], v[22:23]
	v_pk_add_f32 v[164:165], v[164:165], v[164:165] op_sel_hi:[0,1]
	v_pk_mov_b32 v[170:171], v[168:169], v[166:167] op_sel:[1,0]
	v_mov_b32_e32 v169, v167
	v_mul_f32_e32 v164, v16, v16
	v_pk_add_f32 v[166:167], v[170:171], v[168:169]
	v_pk_fma_f32 v[168:169], v[16:17], v[16:17], v[164:165] op_sel_hi:[1,1,0]
	v_mul_f32_e32 v164, v18, v18
	v_pk_add_f32 v[166:167], v[166:167], v[166:167] op_sel_hi:[0,1]
	v_pk_fma_f32 v[170:171], v[18:19], v[18:19], v[164:165] op_sel_hi:[1,1,0]
	v_mul_f32_e32 v168, v12, v12
	v_mul_f32_e32 v170, v13, v13
	v_mul_f32_e32 v166, v14, v14
	v_mul_f32_e32 v164, v15, v15
	v_pk_add_f32 v[168:169], v[168:169], v[170:171]
	v_pk_add_f32 v[164:165], v[166:167], v[164:165]
	v_pk_mul_f32 v[166:167], v[10:11], v[10:11]
	v_pk_add_f32 v[164:165], v[168:169], v[164:165]
	v_pk_mul_f32 v[168:169], v[8:9], v[8:9]
	v_pk_add_f32 v[164:165], v[164:165], v[164:165] op_sel_hi:[0,1]
	v_pk_mov_b32 v[170:171], v[168:169], v[166:167] op_sel:[1,0]
	v_mov_b32_e32 v169, v167
	v_mul_f32_e32 v164, v4, v4
	v_pk_add_f32 v[166:167], v[170:171], v[168:169]
	v_pk_fma_f32 v[168:169], v[4:5], v[4:5], v[164:165] op_sel_hi:[1,1,0]
	v_mul_f32_e32 v164, v6, v6
	v_pk_add_f32 v[166:167], v[166:167], v[166:167] op_sel_hi:[0,1]
	v_pk_fma_f32 v[170:171], v[6:7], v[6:7], v[164:165] op_sel_hi:[1,1,0]
	v_mul_f32_e32 v168, v0, v0
	v_mul_f32_e32 v170, v1, v1
	v_mul_f32_e32 v166, v2, v2
	v_mul_f32_e32 v164, v3, v3
	v_pk_add_f32 v[168:169], v[168:169], v[170:171]
	v_pk_add_f32 v[164:165], v[166:167], v[164:165]
	s_nop 0
	v_pk_add_f32 v[164:165], v[168:169], v[164:165]
	s_nop 0
	v_add_f32_e32 v164, v164, v165
	ds_bpermute_b32 v165, v110, v164
	s_waitcnt lgkmcnt(0)
	v_add_f32_e32 v164, v164, v165
	ds_bpermute_b32 v165, v111, v164
	s_waitcnt lgkmcnt(0)
	v_add_f32_e32 v164, v164, v165
	ds_bpermute_b32 v165, v112, v164
	s_waitcnt lgkmcnt(0)
	v_add_f32_e32 v164, v164, v165
	ds_bpermute_b32 v165, v113, v164
	s_waitcnt lgkmcnt(0)
	v_add_f32_e32 v164, v164, v165
	ds_bpermute_b32 v165, v114, v164
	s_waitcnt lgkmcnt(0)
	v_add_f32_e32 v164, v164, v165
	ds_bpermute_b32 v165, v115, v164
	s_waitcnt lgkmcnt(0)
	v_add_f32_e32 v164, v164, v165
	v_fmamk_f32 v164, v164, 0x3a000000, v252
	v_mul_f32_e32 v165, 0x4b800000, v164
	v_cmp_gt_f32_e32 vcc, s88, v164
	s_nop 1
	v_cndmask_b32_e32 v164, v164, v165, vcc
	v_rsq_f32_e32 v164, v164
	s_nop 0
	v_mul_f32_e32 v165, 0x45800000, v164
	v_cndmask_b32_e32 v164, v164, v165, vcc
	v_pk_mul_f32 v[30:31], v[30:31], v[164:165] op_sel_hi:[1,0]
	v_pk_mul_f32 v[28:29], v[28:29], v[164:165] op_sel_hi:[1,0]
	s_waitcnt vmcnt(23)
	v_pk_mul_f32 v[30:31], v[118:119], v[30:31]
	v_pk_mul_f32 v[28:29], v[116:117], v[28:29]
	s_waitcnt vmcnt(21)
	v_pk_add_f32 v[118:119], v[124:125], 1.0 op_sel_hi:[1,0]
	v_pk_add_f32 v[116:117], v[126:127], 1.0 op_sel_hi:[1,0]
	s_waitcnt vmcnt(19)
	v_pk_fma_f32 v[28:29], v[118:119], v[28:29], v[132:133]
	v_pk_fma_f32 v[30:31], v[116:117], v[30:31], v[134:135]
	v_bfe_u32 v116, v28, 16, 1
	v_add3_u32 v28, v28, v116, s65
	v_bfe_u32 v116, v29, 16, 1
	v_lshrrev_b32_e32 v28, 16, v28
	v_add3_u32 v29, v29, v116, s65
	v_and_or_b32 v28, v29, s61, v28
	s_nop 0
	s_nop 0
	s_nop 0
	v_cvt_pk_bf16_f32 v29, v30, v31
	v_add_co_u32_e32 v30, vcc, s10, v108
	v_pk_mul_f32 v[24:25], v[24:25], v[164:165] op_sel_hi:[1,0]
	s_nop 0
	v_addc_co_u32_e32 v31, vcc, 0, v109, vcc
	v_pk_mul_f32 v[26:27], v[26:27], v[164:165] op_sel_hi:[1,0]
	v_pk_mul_f32 v[24:25], v[120:121], v[24:25]
	v_pk_add_f32 v[108:109], v[128:129], 1.0 op_sel_hi:[1,0]
	global_store_dwordx2 v[30:31], v[28:29], off
	v_pk_mul_f32 v[26:27], v[122:123], v[26:27]
	v_pk_add_f32 v[28:29], v[130:131], 1.0 op_sel_hi:[1,0]
	s_waitcnt vmcnt(19)
	v_pk_fma_f32 v[24:25], v[108:109], v[24:25], v[136:137]
	v_pk_fma_f32 v[26:27], v[28:29], v[26:27], v[138:139]
	v_bfe_u32 v28, v24, 16, 1
	v_add3_u32 v24, v24, v28, s65
	v_bfe_u32 v28, v25, 16, 1
	v_lshrrev_b32_e32 v24, 16, v24
	v_add3_u32 v25, v25, v28, s65
	v_and_or_b32 v24, v25, s61, v24
	v_pk_mul_f32 v[20:21], v[20:21], v[164:165] op_sel_hi:[1,0]
	v_cvt_pk_bf16_f32 v25, v26, v27
	v_pk_mul_f32 v[22:23], v[22:23], v[164:165] op_sel_hi:[1,0]
	s_waitcnt vmcnt(18)
	v_pk_mul_f32 v[20:21], v[140:141], v[20:21]
	s_waitcnt vmcnt(16)
	v_pk_add_f32 v[26:27], v[148:149], 1.0 op_sel_hi:[1,0]
	global_store_dwordx2 v[30:31], v[24:25], off offset:512
	v_pk_mul_f32 v[22:23], v[142:143], v[22:23]
	v_pk_add_f32 v[24:25], v[150:151], 1.0 op_sel_hi:[1,0]
	s_waitcnt vmcnt(15)
	v_pk_fma_f32 v[20:21], v[26:27], v[20:21], v[156:157]
	v_pk_fma_f32 v[22:23], v[24:25], v[22:23], v[158:159]
	v_bfe_u32 v24, v20, 16, 1
	v_add3_u32 v20, v20, v24, s65
	v_bfe_u32 v24, v21, 16, 1
	v_lshrrev_b32_e32 v20, 16, v20
	v_add3_u32 v21, v21, v24, s65
	v_and_or_b32 v20, v21, s61, v20
	v_pk_mul_f32 v[16:17], v[16:17], v[164:165] op_sel_hi:[1,0]
	v_cvt_pk_bf16_f32 v21, v22, v23
	v_pk_mul_f32 v[18:19], v[18:19], v[164:165] op_sel_hi:[1,0]
	v_pk_mul_f32 v[16:17], v[144:145], v[16:17]
	v_pk_add_f32 v[22:23], v[152:153], 1.0 op_sel_hi:[1,0]
	global_store_dwordx2 v[30:31], v[20:21], off offset:1024
	v_pk_mul_f32 v[18:19], v[146:147], v[18:19]
	v_pk_add_f32 v[20:21], v[154:155], 1.0 op_sel_hi:[1,0]
	s_waitcnt vmcnt(15)
	v_pk_fma_f32 v[16:17], v[22:23], v[16:17], v[160:161]
	v_pk_fma_f32 v[18:19], v[20:21], v[18:19], v[162:163]
	v_bfe_u32 v20, v16, 16, 1
	v_add3_u32 v16, v16, v20, s65
	v_bfe_u32 v20, v17, 16, 1
	v_lshrrev_b32_e32 v16, 16, v16
	v_add3_u32 v17, v17, v20, s65
	v_and_or_b32 v16, v17, s61, v16
	v_pk_mul_f32 v[12:13], v[12:13], v[164:165] op_sel_hi:[1,0]
	v_cvt_pk_bf16_f32 v17, v18, v19
	v_pk_mul_f32 v[14:15], v[14:15], v[164:165] op_sel_hi:[1,0]
	s_waitcnt vmcnt(14)
	v_pk_mul_f32 v[12:13], v[72:73], v[12:13]
	s_waitcnt vmcnt(12)
	v_pk_add_f32 v[18:19], v[76:77], 1.0 op_sel_hi:[1,0]
	global_store_dwordx2 v[30:31], v[16:17], off offset:1536
	v_pk_mul_f32 v[14:15], v[74:75], v[14:15]
	v_pk_add_f32 v[16:17], v[78:79], 1.0 op_sel_hi:[1,0]
	s_waitcnt vmcnt(11)
	v_pk_fma_f32 v[12:13], v[18:19], v[12:13], v[68:69]
	v_pk_fma_f32 v[14:15], v[16:17], v[14:15], v[70:71]
	v_bfe_u32 v16, v12, 16, 1
	v_add3_u32 v12, v12, v16, s65
	v_bfe_u32 v16, v13, 16, 1
	v_lshrrev_b32_e32 v12, 16, v12
	v_add3_u32 v13, v13, v16, s65
	v_and_or_b32 v12, v13, s61, v12
	v_pk_mul_f32 v[8:9], v[8:9], v[164:165] op_sel_hi:[1,0]
	v_cvt_pk_bf16_f32 v13, v14, v15
	v_pk_mul_f32 v[10:11], v[10:11], v[164:165] op_sel_hi:[1,0]
	v_pk_mul_f32 v[8:9], v[64:65], v[8:9]
	v_pk_add_f32 v[14:15], v[60:61], 1.0 op_sel_hi:[1,0]
	global_store_dwordx2 v[30:31], v[12:13], off offset:2048
	v_pk_mul_f32 v[10:11], v[66:67], v[10:11]
	v_pk_add_f32 v[12:13], v[62:63], 1.0 op_sel_hi:[1,0]
	s_waitcnt vmcnt(11)
	v_pk_fma_f32 v[8:9], v[14:15], v[8:9], v[56:57]
	v_pk_fma_f32 v[10:11], v[12:13], v[10:11], v[58:59]
	v_bfe_u32 v12, v8, 16, 1
	v_add3_u32 v8, v8, v12, s65
	v_bfe_u32 v12, v9, 16, 1
	v_lshrrev_b32_e32 v8, 16, v8
	v_add3_u32 v9, v9, v12, s65
	v_and_or_b32 v8, v9, s61, v8
	v_pk_mul_f32 v[4:5], v[4:5], v[164:165] op_sel_hi:[1,0]
	v_cvt_pk_bf16_f32 v9, v10, v11
	v_pk_mul_f32 v[6:7], v[6:7], v[164:165] op_sel_hi:[1,0]
	s_waitcnt vmcnt(10)
	v_pk_mul_f32 v[4:5], v[48:49], v[4:5]
	s_waitcnt vmcnt(8)
	v_pk_add_f32 v[10:11], v[52:53], 1.0 op_sel_hi:[1,0]
	global_store_dwordx2 v[30:31], v[8:9], off offset:2560
	v_pk_mul_f32 v[6:7], v[50:51], v[6:7]
	v_pk_add_f32 v[8:9], v[54:55], 1.0 op_sel_hi:[1,0]
	s_waitcnt vmcnt(7)
	v_pk_fma_f32 v[4:5], v[10:11], v[4:5], v[44:45]
	v_pk_fma_f32 v[6:7], v[8:9], v[6:7], v[46:47]
	v_bfe_u32 v8, v4, 16, 1
	v_add3_u32 v4, v4, v8, s65
	v_bfe_u32 v8, v5, 16, 1
	v_lshrrev_b32_e32 v4, 16, v4
	v_add3_u32 v5, v5, v8, s65
	v_and_or_b32 v4, v5, s61, v4
	v_pk_mul_f32 v[0:1], v[0:1], v[164:165] op_sel_hi:[1,0]
	v_cvt_pk_bf16_f32 v5, v6, v7
	v_pk_mul_f32 v[2:3], v[2:3], v[164:165] op_sel_hi:[1,0]
	v_pk_mul_f32 v[0:1], v[40:41], v[0:1]
	v_pk_add_f32 v[6:7], v[36:37], 1.0 op_sel_hi:[1,0]
	global_store_dwordx2 v[30:31], v[4:5], off offset:3072
	v_pk_mul_f32 v[2:3], v[42:43], v[2:3]
	v_pk_add_f32 v[4:5], v[38:39], 1.0 op_sel_hi:[1,0]
	s_waitcnt vmcnt(7)
	v_pk_fma_f32 v[0:1], v[6:7], v[0:1], v[32:33]
	v_pk_fma_f32 v[2:3], v[4:5], v[2:3], v[34:35]
	v_bfe_u32 v4, v0, 16, 1
	v_add3_u32 v0, v0, v4, s65
	v_bfe_u32 v4, v1, 16, 1
	v_lshrrev_b32_e32 v0, 16, v0
	v_add3_u32 v1, v1, v4, s65
	v_and_or_b32 v0, v1, s61, v0
	v_bfe_u32 v1, v2, 16, 1
	v_add3_u32 v1, v2, v1, s65
	v_bfe_u32 v2, v3, 16, 1
	v_lshrrev_b32_e32 v1, 16, v1
	v_add3_u32 v2, v3, v2, s65
	v_and_or_b32 v1, v2, s61, v1
	global_store_dwordx2 v[30:31], v[0:1], off offset:3584
	s_branch .LBB0_1216
